# fused residual+norm epilogues: flat_load/flat_store dwordx2/x4 -> global_load/global_store (no LDS-aperture path, vmcnt only)
# baseline (speedup 1.0000x reference)
;     __device__ __forceinline__ void fused(f32x4 (&acc)[2][2][4][2], const Unit& u, int wr, int wc, int fr, int fq, LAS unsigned char* lds, int tid) const {
;     ...
;             f32x4 gv[2][2];
; #pragma unroll
;             for (int bj = 0; bj < 2; ++bj)
; #pragma unroll
;                 for (int n = 0; n < 2; ++n) gv[bj][n] = *(const f32x4*)(gate + (size_t)cls * MODLD + col0 + bj * HALF + n * 4) * coef;
; #pragma unroll
;             for (int ai = 0; ai < 2; ++ai)
; #pragma unroll
;                 for (int m = 0; m < 4; ++m) { const size_t off = (size_t)(ai * HALF + wr * 64 + m * 16 + fr) * DM + col0; float q = 0.f;
; #pragma unroll
;                     for (int bj = 0; bj < 2; ++bj) { f32x4 b0, b1;
;                         if (BBF) { const u32x4 w = *(const u32x4*)(xb_ + off + bj * HALF);
;                             b0 = (f32x4){__uint_as_float(w.x << 16), __uint_as_float(w.x & 0xffff0000u), __uint_as_float(w.y << 16), __uint_as_float(w.y & 0xffff0000u)};
;                             b1 = (f32x4){__uint_as_float(w.z << 16), __uint_as_float(w.z & 0xffff0000u), __uint_as_float(w.w << 16), __uint_as_float(w.w & 0xffff0000u)}; }
;                         else { b0 = __builtin_nontemporal_load((const f32x4*)(bs_ + off + bj * HALF)); b1 = __builtin_nontemporal_load((const f32x4*)(bs_ + off + bj * HALF + 4)); }
;                         const f32x4 x0 = b0 + gv[bj][0] * acc[ai][bj][m][0], x1 = b1 + gv[bj][1] * acc[ai][bj][m][1]; acc[ai][bj][m][0] = x0; acc[ai][bj][m][1] = x1;
;                         q += ((x0[0] * x0[0] + x0[1] * x0[1]) + (x0[2] * x0[2] + x0[3] * x0[3])) + ((x1[0] * x1[0] + x1[1] * x1[1]) + (x1[2] * x1[2] + x1[3] * x1[3])); }
;                     q += __shfl_xor(q, 16); q += __shfl_xor(q, 32);
;                     if (fq == 0) P[(ai * HALF + wr * 64 + m * 16 + fr) * 4 + wc] = q;
;                     asm volatile("" ::: "memory"); }
.LBB0_479:
	s_add_u32 s28, s94, 0x4000
	s_addc_u32 s29, s95, 0
	s_add_u32 s30, s94, 0x5000
	s_addc_u32 s31, s95, 0
	s_lshl_b32 s14, s9, 5
	s_add_u32 s2, s94, 0x83800
	s_addc_u32 s3, s95, 0
	v_readlane_b32 s44, v254, 8
	s_add_u32 s38, s94, 0xff00000
	v_readlane_b32 s48, v254, 12
	v_readlane_b32 s49, v254, 13
	v_readlane_b32 s36, v254, 60
	s_addc_u32 s39, s95, 0
	s_mov_b32 s40, 0.5
	s_mov_b64 s[34:35], s[48:49]
	v_readlane_b32 s37, v254, 61
	s_mov_b64 s[26:27], s[18:19]
	s_mov_b64 s[12:13], s[92:93]
	s_waitcnt vmcnt(0)
	s_barrier
	s_ashr_i32 s23, s22, 31
	s_lshr_b32 s12, s23, 28
	s_add_i32 s12, s22, s12
	s_ashr_i32 s13, s12, 4
	s_lshl_b32 s12, s24, 8
	s_or_b32 s12, s12, s14
	v_lshl_or_b32 v130, v150, 3, s12
	s_mul_hi_i32 s12, s13, 0x9000
	s_mul_i32 s13, s13, 0x9000
	s_add_u32 s4, s4, s13
	v_ashrrev_i32_e32 v131, 31, v130
	s_addc_u32 s5, s5, s12
	v_lshlrev_b64 v[132:133], 2, v[130:131]
	v_lshl_add_u64 v[148:149], s[4:5], 0, v[132:133]
	s_lshl_b64 s[4:5], s[22:23], 20
	s_add_u32 s4, s76, s4
	s_addc_u32 s5, s77, s5
	v_ashrrev_i32_e32 v139, 31, v138
	global_load_dwordx4 v[134:137], v[148:149], off
	global_load_dwordx4 v[140:143], v[148:149], off offset:16
	global_load_dwordx4 v[144:147], v[148:149], off offset:512
	global_load_dwordx4 v[152:155], v[148:149], off offset:528
	v_lshl_add_u64 v[158:159], s[4:5], 0, v[132:133]
	v_lshlrev_b64 v[148:149], 12, v[138:139]
	v_lshl_add_u64 v[148:149], v[158:159], 0, v[148:149]
	global_load_dwordx4 v[180:183], v[148:149], off nt
	global_load_dwordx4 v[184:187], v[148:149], off offset:16 nt
	global_load_dwordx4 v[188:191], v[148:149], off offset:512 nt
	global_load_dwordx4 v[192:195], v[148:149], off offset:528 nt
	v_mbcnt_lo_u32_b32 v148, -1, 0
	v_mbcnt_hi_u32_b32 v148, -1, v148
	v_and_b32_e32 v151, 64, v148
	v_xor_b32_e32 v149, 16, v148
	v_add_u32_e32 v151, 64, v151
	v_cmp_lt_i32_e32 vcc, v149, v151
	s_lshl_b32 s4, s9, 2
	s_add_i32 s9, s4, 0
	v_cndmask_b32_e32 v149, v148, v149, vcc
	v_lshlrev_b32_e32 v176, 2, v149
	v_readlane_b32 s45, v254, 9
	v_readlane_b32 s46, v254, 10
	v_readlane_b32 s47, v254, 11
	v_readlane_b32 s50, v254, 14
	v_readlane_b32 s51, v254, 15
	v_readlane_b32 s52, v254, 16
	v_readlane_b32 s53, v254, 17
	v_readlane_b32 s54, v254, 18
	v_readlane_b32 s55, v254, 19
	v_readlane_b32 s56, v254, 20
	v_readlane_b32 s57, v254, 21
	v_readlane_b32 s58, v254, 22
	v_readlane_b32 s59, v254, 23
	s_waitcnt vmcnt(0) lgkmcnt(0)
	v_pk_mul_f32 v[164:165], v[134:135], s[40:41] op_sel_hi:[1,0]
	v_pk_mul_f32 v[160:161], v[136:137], s[40:41] op_sel_hi:[1,0]
	v_pk_mul_f32 v[162:163], v[140:141], s[40:41] op_sel_hi:[1,0]
	v_pk_mul_f32 v[174:175], v[142:143], s[40:41] op_sel_hi:[1,0]
	v_pk_mul_f32 v[170:171], s[40:41], v[144:145] op_sel_hi:[0,1]
	v_pk_mul_f32 v[172:173], s[40:41], v[146:147] op_sel_hi:[0,1]
	v_pk_mul_f32 v[166:167], s[40:41], v[152:153] op_sel_hi:[0,1]
	v_pk_mul_f32 v[168:169], s[40:41], v[154:155] op_sel_hi:[0,1]
	v_pk_fma_f32 v[126:127], v[126:127], v[160:161], v[182:183]
	v_pk_fma_f32 v[124:125], v[124:125], v[164:165], v[180:181]
	v_pk_fma_f32 v[122:123], v[122:123], v[174:175], v[186:187]
	v_pk_fma_f32 v[120:121], v[120:121], v[162:163], v[184:185]
	v_pk_fma_f32 v[118:119], v[118:119], v[172:173], v[190:191]
	v_pk_fma_f32 v[116:117], v[116:117], v[170:171], v[188:189]
	v_pk_fma_f32 v[114:115], v[114:115], v[168:169], v[194:195]
	v_pk_fma_f32 v[112:113], v[112:113], v[166:167], v[192:193]
	v_mul_f32_e32 v134, v125, v125
	v_mul_f32_e32 v135, v127, v127
	v_mul_f32_e32 v136, v121, v121
	v_mul_f32_e32 v137, v123, v123
	v_mul_f32_e32 v140, v117, v117
	v_mul_f32_e32 v141, v119, v119
	v_mul_f32_e32 v142, v113, v113
	v_mul_f32_e32 v143, v115, v115
	v_fmac_f32_e32 v134, v124, v124
	v_fmac_f32_e32 v135, v126, v126
	v_fmac_f32_e32 v136, v120, v120
	v_fmac_f32_e32 v137, v122, v122
	v_fmac_f32_e32 v140, v116, v116
	v_fmac_f32_e32 v141, v118, v118
	v_fmac_f32_e32 v142, v112, v112
	v_fmac_f32_e32 v143, v114, v114
	v_add_f32_e32 v134, v134, v135
	v_add_f32_e32 v135, v136, v137
	v_add_f32_e32 v136, v140, v141
	v_add_f32_e32 v137, v142, v143
	v_add_f32_e32 v134, v134, v135
	v_add_f32_e32 v135, v136, v137
	v_add_f32_e32 v134, v134, v135
	ds_bpermute_b32 v135, v176, v134
	v_xor_b32_e32 v136, 32, v148
	v_cmp_lt_i32_e32 vcc, v136, v151
	s_waitcnt lgkmcnt(0)
	v_add_f32_e32 v134, v134, v135
	v_cndmask_b32_e32 v136, v148, v136, vcc
	v_lshlrev_b32_e32 v177, 2, v136
	ds_bpermute_b32 v135, v177, v134
	v_cmp_eq_u32_e32 vcc, 0, v150
	s_and_saveexec_b64 s[4:5], vcc
	s_cbranch_execz .LBB0_481
	v_lshl_add_u32 v136, v138, 4, s9
	s_waitcnt lgkmcnt(0)
	v_add_f32_e32 v134, v134, v135
	ds_write_b32 v136, v134
.LBB0_481:
	s_or_b64 exec, exec, s[4:5]
	v_or_b32_e32 v134, 16, v138
	s_waitcnt lgkmcnt(0)
	v_ashrrev_i32_e32 v135, 31, v134
	v_lshlrev_b64 v[136:137], 12, v[134:135]
	v_lshl_add_u64 v[136:137], v[158:159], 0, v[136:137]
	global_load_dwordx4 v[140:143], v[136:137], off nt
	global_load_dwordx4 v[144:147], v[136:137], off offset:16 nt
	global_load_dwordx4 v[148:151], v[136:137], off offset:512 nt
	global_load_dwordx4 v[152:155], v[136:137], off offset:528 nt
	s_waitcnt vmcnt(0) lgkmcnt(0)
	v_pk_fma_f32 v[110:111], v[110:111], v[160:161], v[142:143]
	v_pk_fma_f32 v[108:109], v[108:109], v[164:165], v[140:141]
	v_pk_fma_f32 v[106:107], v[106:107], v[174:175], v[146:147]
	v_pk_fma_f32 v[104:105], v[104:105], v[162:163], v[144:145]
	v_pk_fma_f32 v[102:103], v[102:103], v[172:173], v[150:151]
	v_pk_fma_f32 v[100:101], v[100:101], v[170:171], v[148:149]
	v_pk_fma_f32 v[98:99], v[98:99], v[168:169], v[154:155]
	v_pk_fma_f32 v[96:97], v[96:97], v[166:167], v[152:153]
	v_mul_f32_e32 v136, v109, v109
	v_mul_f32_e32 v137, v111, v111
	v_mul_f32_e32 v140, v105, v105
	v_mul_f32_e32 v141, v107, v107
	v_mul_f32_e32 v142, v101, v101
	v_mul_f32_e32 v143, v103, v103
	v_mul_f32_e32 v144, v97, v97
	v_mul_f32_e32 v145, v99, v99
	v_fmac_f32_e32 v136, v108, v108
	v_fmac_f32_e32 v137, v110, v110
	v_fmac_f32_e32 v140, v104, v104
	v_fmac_f32_e32 v141, v106, v106
	v_fmac_f32_e32 v142, v100, v100
	v_fmac_f32_e32 v143, v102, v102
	v_fmac_f32_e32 v144, v96, v96
	v_fmac_f32_e32 v145, v98, v98
	v_add_f32_e32 v136, v136, v137
	v_add_f32_e32 v137, v140, v141
	v_add_f32_e32 v140, v142, v143
	v_add_f32_e32 v141, v144, v145
	v_add_f32_e32 v136, v136, v137
	v_add_f32_e32 v137, v140, v141
	v_add_f32_e32 v136, v136, v137
	ds_bpermute_b32 v137, v176, v136
	s_waitcnt lgkmcnt(0)
	v_add_f32_e32 v136, v136, v137
	ds_bpermute_b32 v137, v177, v136
	s_and_saveexec_b64 s[4:5], vcc
	s_cbranch_execz .LBB0_483
	v_lshl_add_u32 v140, v134, 4, s9
	s_waitcnt lgkmcnt(0)
	v_add_f32_e32 v136, v136, v137
	ds_write_b32 v140, v136
;     __device__ __forceinline__ void fused(f32x4 (&acc)[2][2][4][2], const Unit& u, int wr, int wc, int fr, int fq, LAS unsigned char* lds, int tid) const {
;     ...
;                 for (int m = 0; m < 4; ++m) { const size_t off = (size_t)(ai * HALF + wr * 64 + m * 16 + fr) * DM + col0; float q = 0.f;
; #pragma unroll
;                     for (int bj = 0; bj < 2; ++bj) { f32x4 b0, b1;
;                         if (BBF) { const u32x4 w = *(const u32x4*)(xb_ + off + bj * HALF);
;                             b0 = (f32x4){__uint_as_float(w.x << 16), __uint_as_float(w.x & 0xffff0000u), __uint_as_float(w.y << 16), __uint_as_float(w.y & 0xffff0000u)};
;                             b1 = (f32x4){__uint_as_float(w.z << 16), __uint_as_float(w.z & 0xffff0000u), __uint_as_float(w.w << 16), __uint_as_float(w.w & 0xffff0000u)}; }
;                         else { b0 = __builtin_nontemporal_load((const f32x4*)(bs_ + off + bj * HALF)); b1 = __builtin_nontemporal_load((const f32x4*)(bs_ + off + bj * HALF + 4)); }
;                         const f32x4 x0 = b0 + gv[bj][0] * acc[ai][bj][m][0], x1 = b1 + gv[bj][1] * acc[ai][bj][m][1]; acc[ai][bj][m][0] = x0; acc[ai][bj][m][1] = x1;
;                         q += ((x0[0] * x0[0] + x0[1] * x0[1]) + (x0[2] * x0[2] + x0[3] * x0[3])) + ((x1[0] * x1[0] + x1[1] * x1[1]) + (x1[2] * x1[2] + x1[3] * x1[3])); }
;                     q += __shfl_xor(q, 16); q += __shfl_xor(q, 32);
;                     if (fq == 0) P[(ai * HALF + wr * 64 + m * 16 + fr) * 4 + wc] = q;
;                     asm volatile("" ::: "memory"); }
.LBB0_483:
	s_or_b64 exec, exec, s[4:5]
	v_or_b32_e32 v140, 32, v138
	v_ashrrev_i32_e32 v141, 31, v140
	s_waitcnt lgkmcnt(0)
	v_lshlrev_b64 v[136:137], 12, v[140:141]
	v_lshl_add_u64 v[136:137], v[158:159], 0, v[136:137]
	global_load_dwordx4 v[142:145], v[136:137], off nt
	global_load_dwordx4 v[146:149], v[136:137], off offset:16 nt
	global_load_dwordx4 v[150:153], v[136:137], off offset:512 nt
	global_load_dwordx4 v[154:157], v[136:137], off offset:528 nt
	s_waitcnt vmcnt(0) lgkmcnt(0)
	v_pk_fma_f32 v[94:95], v[94:95], v[160:161], v[144:145]
	v_pk_fma_f32 v[92:93], v[92:93], v[164:165], v[142:143]
	v_pk_fma_f32 v[90:91], v[90:91], v[174:175], v[148:149]
	v_pk_fma_f32 v[88:89], v[88:89], v[162:163], v[146:147]
	v_pk_fma_f32 v[86:87], v[86:87], v[172:173], v[152:153]
	v_pk_fma_f32 v[84:85], v[84:85], v[170:171], v[150:151]
	v_pk_fma_f32 v[82:83], v[82:83], v[168:169], v[156:157]
	v_pk_fma_f32 v[80:81], v[80:81], v[166:167], v[154:155]
	v_mul_f32_e32 v136, v93, v93
	v_mul_f32_e32 v137, v95, v95
	v_mul_f32_e32 v142, v89, v89
	v_mul_f32_e32 v143, v91, v91
	v_mul_f32_e32 v144, v85, v85
	v_mul_f32_e32 v145, v87, v87
	v_mul_f32_e32 v146, v81, v81
	v_mul_f32_e32 v147, v83, v83
	v_fmac_f32_e32 v136, v92, v92
	v_fmac_f32_e32 v137, v94, v94
	v_fmac_f32_e32 v142, v88, v88
	v_fmac_f32_e32 v143, v90, v90
	v_fmac_f32_e32 v144, v84, v84
	v_fmac_f32_e32 v145, v86, v86
	v_fmac_f32_e32 v146, v80, v80
	v_fmac_f32_e32 v147, v82, v82
	v_add_f32_e32 v136, v136, v137
	v_add_f32_e32 v137, v142, v143
	v_add_f32_e32 v142, v144, v145
	v_add_f32_e32 v143, v146, v147
	v_add_f32_e32 v136, v136, v137
	v_add_f32_e32 v137, v142, v143
	v_add_f32_e32 v136, v136, v137
	ds_bpermute_b32 v137, v176, v136
	s_waitcnt lgkmcnt(0)
	v_add_f32_e32 v136, v136, v137
	ds_bpermute_b32 v137, v177, v136
	s_and_saveexec_b64 s[4:5], vcc
	s_cbranch_execz .LBB0_485
	v_lshl_add_u32 v142, v140, 4, s9
	s_waitcnt lgkmcnt(0)
	v_add_f32_e32 v136, v136, v137
	ds_write_b32 v142, v136
.LBB0_485:
	s_or_b64 exec, exec, s[4:5]
	v_or_b32_e32 v136, 48, v138
	s_waitcnt lgkmcnt(0)
	v_ashrrev_i32_e32 v137, 31, v136
	v_lshlrev_b64 v[142:143], 12, v[136:137]
	v_lshl_add_u64 v[154:155], v[158:159], 0, v[142:143]
	global_load_dwordx4 v[142:145], v[154:155], off nt
	global_load_dwordx4 v[146:149], v[154:155], off offset:16 nt
	global_load_dwordx4 v[150:153], v[154:155], off offset:512 nt
	s_nop 0
	global_load_dwordx4 v[154:157], v[154:155], off offset:528 nt
	s_waitcnt vmcnt(0) lgkmcnt(0)
	v_pk_fma_f32 v[78:79], v[78:79], v[160:161], v[144:145]
	v_pk_fma_f32 v[76:77], v[76:77], v[164:165], v[142:143]
	v_pk_fma_f32 v[74:75], v[74:75], v[174:175], v[148:149]
	v_pk_fma_f32 v[72:73], v[72:73], v[162:163], v[146:147]
	v_pk_fma_f32 v[70:71], v[70:71], v[172:173], v[152:153]
	v_pk_fma_f32 v[68:69], v[68:69], v[170:171], v[150:151]
	v_pk_fma_f32 v[66:67], v[66:67], v[168:169], v[156:157]
	v_pk_fma_f32 v[64:65], v[64:65], v[166:167], v[154:155]
	v_mul_f32_e32 v142, v77, v77
	v_mul_f32_e32 v143, v79, v79
	v_mul_f32_e32 v144, v73, v73
	v_mul_f32_e32 v145, v75, v75
	v_mul_f32_e32 v146, v69, v69
	v_mul_f32_e32 v147, v71, v71
	v_mul_f32_e32 v148, v65, v65
	v_mul_f32_e32 v149, v67, v67
	v_fmac_f32_e32 v142, v76, v76
	v_fmac_f32_e32 v143, v78, v78
	v_fmac_f32_e32 v144, v72, v72
	v_fmac_f32_e32 v145, v74, v74
	v_fmac_f32_e32 v146, v68, v68
	v_fmac_f32_e32 v147, v70, v70
	v_fmac_f32_e32 v148, v64, v64
	v_fmac_f32_e32 v149, v66, v66
	v_add_f32_e32 v142, v142, v143
	v_add_f32_e32 v143, v144, v145
	v_add_f32_e32 v144, v146, v147
	v_add_f32_e32 v145, v148, v149
	v_add_f32_e32 v142, v142, v143
	v_add_f32_e32 v143, v144, v145
	v_add_f32_e32 v142, v142, v143
	ds_bpermute_b32 v143, v176, v142
	s_waitcnt lgkmcnt(0)
	v_add_f32_e32 v142, v142, v143
	ds_bpermute_b32 v143, v177, v142
	s_and_saveexec_b64 s[4:5], vcc
	s_cbranch_execz .LBB0_487
	v_lshl_add_u32 v144, v136, 4, s9
	s_waitcnt lgkmcnt(0)
	v_add_f32_e32 v142, v142, v143
	ds_write_b32 v144, v142
.LBB0_487:
	s_or_b64 exec, exec, s[4:5]
	v_add_u32_e32 v142, 0x80, v138
	s_waitcnt lgkmcnt(0)
	v_ashrrev_i32_e32 v143, 31, v142
	v_lshlrev_b64 v[144:145], 12, v[142:143]
	v_lshl_add_u64 v[156:157], v[158:159], 0, v[144:145]
	global_load_dwordx4 v[144:147], v[156:157], off nt
	global_load_dwordx4 v[148:151], v[156:157], off offset:16 nt
	global_load_dwordx4 v[152:155], v[156:157], off offset:512 nt
	global_load_dwordx4 v[180:183], v[156:157], off offset:528 nt
	s_waitcnt vmcnt(0) lgkmcnt(0)
	v_pk_fma_f32 v[62:63], v[62:63], v[160:161], v[146:147]
	v_pk_fma_f32 v[60:61], v[60:61], v[164:165], v[144:145]
	v_pk_fma_f32 v[58:59], v[58:59], v[174:175], v[150:151]
	v_pk_fma_f32 v[56:57], v[56:57], v[162:163], v[148:149]
	v_pk_fma_f32 v[54:55], v[54:55], v[172:173], v[154:155]
	v_pk_fma_f32 v[52:53], v[52:53], v[170:171], v[152:153]
	v_pk_fma_f32 v[50:51], v[50:51], v[168:169], v[182:183]
	v_pk_fma_f32 v[48:49], v[48:49], v[166:167], v[180:181]
	v_mul_f32_e32 v144, v61, v61
	v_mul_f32_e32 v145, v63, v63
	v_mul_f32_e32 v146, v57, v57
	v_mul_f32_e32 v147, v59, v59
	v_mul_f32_e32 v148, v53, v53
	v_mul_f32_e32 v149, v55, v55
	v_mul_f32_e32 v150, v49, v49
	v_mul_f32_e32 v151, v51, v51
	v_fmac_f32_e32 v144, v60, v60
	v_fmac_f32_e32 v145, v62, v62
	v_fmac_f32_e32 v146, v56, v56
	v_fmac_f32_e32 v147, v58, v58
	v_fmac_f32_e32 v148, v52, v52
	v_fmac_f32_e32 v149, v54, v54
	v_fmac_f32_e32 v150, v48, v48
	v_fmac_f32_e32 v151, v50, v50
	v_add_f32_e32 v144, v144, v145
	v_add_f32_e32 v145, v146, v147
	v_add_f32_e32 v146, v148, v149
	v_add_f32_e32 v147, v150, v151
	v_add_f32_e32 v144, v144, v145
	v_add_f32_e32 v145, v146, v147
	v_add_f32_e32 v144, v144, v145
	ds_bpermute_b32 v145, v176, v144
	s_waitcnt lgkmcnt(0)
	v_add_f32_e32 v144, v144, v145
	ds_bpermute_b32 v145, v177, v144
	s_and_saveexec_b64 s[4:5], vcc
	s_cbranch_execz .LBB0_489
	v_lshl_add_u32 v146, v142, 4, s9
	s_waitcnt lgkmcnt(0)
	v_add_f32_e32 v144, v144, v145
	ds_write_b32 v146, v144
;     __device__ __forceinline__ void fused(f32x4 (&acc)[2][2][4][2], const Unit& u, int wr, int wc, int fr, int fq, LAS unsigned char* lds, int tid) const {
;     ...
;                 for (int m = 0; m < 4; ++m) { const size_t off = (size_t)(ai * HALF + wr * 64 + m * 16 + fr) * DM + col0; float q = 0.f;
; #pragma unroll
;                     for (int bj = 0; bj < 2; ++bj) { f32x4 b0, b1;
;                         if (BBF) { const u32x4 w = *(const u32x4*)(xb_ + off + bj * HALF);
;                             b0 = (f32x4){__uint_as_float(w.x << 16), __uint_as_float(w.x & 0xffff0000u), __uint_as_float(w.y << 16), __uint_as_float(w.y & 0xffff0000u)};
;                             b1 = (f32x4){__uint_as_float(w.z << 16), __uint_as_float(w.z & 0xffff0000u), __uint_as_float(w.w << 16), __uint_as_float(w.w & 0xffff0000u)}; }
;                         else { b0 = __builtin_nontemporal_load((const f32x4*)(bs_ + off + bj * HALF)); b1 = __builtin_nontemporal_load((const f32x4*)(bs_ + off + bj * HALF + 4)); }
;                         const f32x4 x0 = b0 + gv[bj][0] * acc[ai][bj][m][0], x1 = b1 + gv[bj][1] * acc[ai][bj][m][1]; acc[ai][bj][m][0] = x0; acc[ai][bj][m][1] = x1;
;                         q += ((x0[0] * x0[0] + x0[1] * x0[1]) + (x0[2] * x0[2] + x0[3] * x0[3])) + ((x1[0] * x1[0] + x1[1] * x1[1]) + (x1[2] * x1[2] + x1[3] * x1[3])); }
;                     q += __shfl_xor(q, 16); q += __shfl_xor(q, 32);
;                     if (fq == 0) P[(ai * HALF + wr * 64 + m * 16 + fr) * 4 + wc] = q;
;                     asm volatile("" ::: "memory"); }
.LBB0_489:
	s_or_b64 exec, exec, s[4:5]
	v_add_u32_e32 v144, 0x90, v138
	s_waitcnt lgkmcnt(0)
	v_ashrrev_i32_e32 v145, 31, v144
	v_lshlrev_b64 v[146:147], 12, v[144:145]
	v_lshl_add_u64 v[180:181], v[158:159], 0, v[146:147]
	global_load_dwordx4 v[146:149], v[180:181], off nt
	global_load_dwordx4 v[150:153], v[180:181], off offset:16 nt
	global_load_dwordx4 v[154:157], v[180:181], off offset:512 nt
	s_nop 0
	global_load_dwordx4 v[180:183], v[180:181], off offset:528 nt
	s_waitcnt vmcnt(0) lgkmcnt(0)
	v_pk_fma_f32 v[46:47], v[46:47], v[160:161], v[148:149]
	v_pk_fma_f32 v[44:45], v[44:45], v[164:165], v[146:147]
	v_pk_fma_f32 v[42:43], v[42:43], v[174:175], v[152:153]
	v_pk_fma_f32 v[40:41], v[40:41], v[162:163], v[150:151]
	v_pk_fma_f32 v[38:39], v[38:39], v[172:173], v[156:157]
	v_pk_fma_f32 v[36:37], v[36:37], v[170:171], v[154:155]
	v_pk_fma_f32 v[34:35], v[34:35], v[168:169], v[182:183]
	v_pk_fma_f32 v[32:33], v[32:33], v[166:167], v[180:181]
	v_mul_f32_e32 v146, v45, v45
	v_mul_f32_e32 v147, v47, v47
	v_mul_f32_e32 v148, v41, v41
	v_mul_f32_e32 v149, v43, v43
	v_mul_f32_e32 v150, v37, v37
	v_mul_f32_e32 v151, v39, v39
	v_mul_f32_e32 v152, v33, v33
	v_mul_f32_e32 v153, v35, v35
	v_fmac_f32_e32 v146, v44, v44
	v_fmac_f32_e32 v147, v46, v46
	v_fmac_f32_e32 v148, v40, v40
	v_fmac_f32_e32 v149, v42, v42
	v_fmac_f32_e32 v150, v36, v36
	v_fmac_f32_e32 v151, v38, v38
	v_fmac_f32_e32 v152, v32, v32
	v_fmac_f32_e32 v153, v34, v34
	v_add_f32_e32 v146, v146, v147
	v_add_f32_e32 v147, v148, v149
	v_add_f32_e32 v148, v150, v151
	v_add_f32_e32 v149, v152, v153
	v_add_f32_e32 v146, v146, v147
	v_add_f32_e32 v147, v148, v149
	v_add_f32_e32 v146, v146, v147
	ds_bpermute_b32 v147, v176, v146
	s_waitcnt lgkmcnt(0)
	v_add_f32_e32 v146, v146, v147
	ds_bpermute_b32 v147, v177, v146
	s_and_saveexec_b64 s[4:5], vcc
	s_cbranch_execz .LBB0_491
	v_lshl_add_u32 v148, v144, 4, s9
	s_waitcnt lgkmcnt(0)
	v_add_f32_e32 v146, v146, v147
	ds_write_b32 v148, v146
.LBB0_491:
	s_or_b64 exec, exec, s[4:5]
	v_add_u32_e32 v146, 0xa0, v138
	s_waitcnt lgkmcnt(0)
	v_ashrrev_i32_e32 v147, 31, v146
	v_lshlrev_b64 v[148:149], 12, v[146:147]
	v_lshl_add_u64 v[152:153], v[158:159], 0, v[148:149]
	global_load_dwordx4 v[148:151], v[152:153], off nt
	global_load_dwordx4 v[180:183], v[152:153], off offset:16 nt
	global_load_dwordx4 v[184:187], v[152:153], off offset:512 nt
	global_load_dwordx4 v[188:191], v[152:153], off offset:528 nt
	s_waitcnt vmcnt(0) lgkmcnt(0)
	v_pk_fma_f32 v[150:151], v[30:31], v[160:161], v[150:151]
	v_pk_fma_f32 v[154:155], v[28:29], v[164:165], v[148:149]
	v_pk_fma_f32 v[148:149], v[26:27], v[174:175], v[182:183]
	v_pk_fma_f32 v[152:153], v[24:25], v[162:163], v[180:181]
	v_pk_fma_f32 v[22:23], v[22:23], v[172:173], v[186:187]
	v_pk_fma_f32 v[20:21], v[20:21], v[170:171], v[184:185]
	v_pk_fma_f32 v[18:19], v[18:19], v[168:169], v[190:191]
	v_pk_fma_f32 v[16:17], v[16:17], v[166:167], v[188:189]
	v_mul_f32_e32 v24, v155, v155
	v_mul_f32_e32 v25, v151, v151
	v_mul_f32_e32 v26, v153, v153
	v_mul_f32_e32 v27, v149, v149
	v_mul_f32_e32 v28, v21, v21
	v_mul_f32_e32 v29, v23, v23
	v_mul_f32_e32 v30, v17, v17
	v_mul_f32_e32 v31, v19, v19
	v_fmac_f32_e32 v24, v154, v154
	v_fmac_f32_e32 v25, v150, v150
	v_fmac_f32_e32 v26, v152, v152
	v_fmac_f32_e32 v27, v148, v148
	v_fmac_f32_e32 v28, v20, v20
	v_fmac_f32_e32 v29, v22, v22
	v_fmac_f32_e32 v30, v16, v16
	v_fmac_f32_e32 v31, v18, v18
	v_add_f32_e32 v24, v24, v25
	v_add_f32_e32 v25, v26, v27
	v_add_f32_e32 v26, v28, v29
	v_add_f32_e32 v27, v30, v31
	v_add_f32_e32 v24, v24, v25
	v_add_f32_e32 v25, v26, v27
	v_add_f32_e32 v24, v24, v25
	ds_bpermute_b32 v25, v176, v24
	s_waitcnt lgkmcnt(0)
	v_add_f32_e32 v24, v24, v25
	ds_bpermute_b32 v25, v177, v24
	s_and_saveexec_b64 s[4:5], vcc
	s_cbranch_execz .LBB0_493
	v_lshl_add_u32 v26, v146, 4, s9
	s_waitcnt lgkmcnt(0)
	v_add_f32_e32 v24, v24, v25
	ds_write_b32 v26, v24
.LBB0_493:
	s_or_b64 exec, exec, s[4:5]
	v_add_u32_e32 v156, 0xb0, v138
	v_ashrrev_i32_e32 v157, 31, v156
	s_waitcnt lgkmcnt(0)
	v_lshlrev_b64 v[24:25], 12, v[156:157]
	v_lshl_add_u64 v[158:159], v[158:159], 0, v[24:25]
	global_load_dwordx4 v[24:27], v[158:159], off nt
	global_load_dwordx4 v[28:31], v[158:159], off offset:16 nt
	global_load_dwordx4 v[180:183], v[158:159], off offset:512 nt
	global_load_dwordx4 v[184:187], v[158:159], off offset:528 nt
	s_waitcnt vmcnt(0) lgkmcnt(0)
	v_pk_fma_f32 v[160:161], v[14:15], v[160:161], v[26:27]
	v_pk_fma_f32 v[164:165], v[12:13], v[164:165], v[24:25]
	v_pk_fma_f32 v[158:159], v[10:11], v[174:175], v[30:31]
	v_pk_fma_f32 v[162:163], v[8:9], v[162:163], v[28:29]
	v_pk_fma_f32 v[24:25], v[6:7], v[172:173], v[182:183]
	v_pk_fma_f32 v[28:29], v[4:5], v[170:171], v[180:181]
	v_pk_fma_f32 v[26:27], v[2:3], v[168:169], v[186:187]
	v_pk_fma_f32 v[30:31], v[0:1], v[166:167], v[184:185]
	v_mul_f32_e32 v0, v165, v165
	v_mul_f32_e32 v1, v161, v161
	v_mul_f32_e32 v2, v163, v163
	v_mul_f32_e32 v3, v159, v159
	v_mul_f32_e32 v4, v29, v29
	v_mul_f32_e32 v5, v25, v25
	v_mul_f32_e32 v6, v31, v31
	v_mul_f32_e32 v7, v27, v27
	v_fmac_f32_e32 v0, v164, v164
	v_fmac_f32_e32 v1, v160, v160
	v_fmac_f32_e32 v2, v162, v162
	v_fmac_f32_e32 v3, v158, v158
	v_fmac_f32_e32 v4, v28, v28
	v_fmac_f32_e32 v5, v24, v24
	v_fmac_f32_e32 v6, v30, v30
	v_fmac_f32_e32 v7, v26, v26
	v_add_f32_e32 v0, v0, v1
	v_add_f32_e32 v1, v2, v3
	v_add_f32_e32 v2, v4, v5
	v_add_f32_e32 v3, v6, v7
	v_add_f32_e32 v0, v0, v1
	v_add_f32_e32 v1, v2, v3
	v_add_f32_e32 v0, v0, v1
	ds_bpermute_b32 v1, v176, v0
	s_waitcnt lgkmcnt(0)
	v_add_f32_e32 v0, v0, v1
	ds_bpermute_b32 v1, v177, v0
	s_and_saveexec_b64 s[4:5], vcc
	s_cbranch_execz .LBB0_495
	v_lshl_add_u32 v2, v156, 4, s9
	s_waitcnt lgkmcnt(0)
	v_add_f32_e32 v0, v0, v1
	ds_write_b32 v2, v0

; __device__ __forceinline__ unsigned cvt_pk_bf16(float lo, float hi) { unsigned r; asm volatile("v_cvt_pk_bf16_f32 %0, %1, %2" : "=v"(r) : "v"(lo), "v"(hi)); return r; }
;     __device__ __forceinline__ void fused(f32x4 (&acc)[2][2][4][2], const Unit& u, int wr, int wc, int fr, int fq, LAS unsigned char* lds, int tid) const {
;     ...
;         for (int bj = 0; bj < 2; ++bj) { const int c = col0 + bj * HALF;
;             const f32x4 g0 = *(const f32x4*)(g + c), g1 = *(const f32x4*)(g + c + 4);
;             f32x4 sc0 = {0.f, 0.f, 0.f, 0.f}, sc1 = sc0, sh0 = sc0, sh1 = sc0;
;             if (MODE == 0) { sc0 = *(const f32x4*)(scale + (size_t)cls * MODLD + c) + 1.0f; sc1 = *(const f32x4*)(scale + (size_t)cls * MODLD + c + 4) + 1.0f;
;                 sh0 = *(const f32x4*)(shift + (size_t)cls * MODLD + c); sh1 = *(const f32x4*)(shift + (size_t)cls * MODLD + c + 4); }
; #pragma unroll
;             for (int ai = 0; ai < 2; ++ai)
; #pragma unroll
;                 for (int m = 0; m < 4; ++m) { const int r = ai * HALF + wr * 64 + m * 16 + fr; const size_t off = (size_t)r * DM + c; const float rs = S[r];
;                     const f32x4 x0 = acc[ai][bj][m][0], x1 = acc[ai][bj][m][1]; const f32x4 y0 = x0 * rs * g0, y1 = x1 * rs * g1;
;                     if (MODE == 0) { { u32x4 wx; wx.x = cvt_pk_bf16(x0[0], x0[1]); wx.y = cvt_pk_bf16(x0[2], x0[3]); wx.z = cvt_pk_bf16(x1[0], x1[1]); wx.w = cvt_pk_bf16(x1[2], x1[3]); *(u32x4*)(xb_ + off) = wx; }
;                         const f32x4 z0 = y0 * sc0 + sh0, z1 = y1 * sc1 + sh1;
;                         u32x4 w; w.x = cvt_pk_bf16(z0[0], z0[1]); w.y = cvt_pk_bf16(z0[2], z0[3]); w.z = cvt_pk_bf16(z1[0], z1[1]); w.w = cvt_pk_bf16(z1[2], z1[3]);
;                         *(u32x4*)(XN + (size_t)u.pm * BM * DM + off) = w; }
;                     else { *(f32x4*)(out_ + off) = y0; *(f32x4*)(out_ + off + 4) = y1; } }
;             asm volatile("" ::: "memory"); }
.LBB0_522:
	s_or_b64 exec, exec, s[24:25]
	s_lshl_b64 s[2:3], s[2:3], 1
	s_add_u32 s2, s36, s2
	s_addc_u32 s3, s37, s3
	s_add_u32 s4, s30, s13
	s_addc_u32 s5, s31, s12
	s_add_u32 s14, s28, s13
	s_waitcnt lgkmcnt(0)
	s_barrier
	v_lshl_add_u64 v[166:167], s[34:35], 0, v[132:133]
	v_lshl_add_u64 v[168:169], s[4:5], 0, v[132:133]
	s_addc_u32 s15, s29, s12
	global_load_dwordx4 v[12:15], v[166:167], off
	global_load_dwordx4 v[8:11], v[166:167], off offset:16
	global_load_dwordx4 v[170:173], v[168:169], off
	global_load_dwordx4 v[174:177], v[168:169], off offset:16
	v_lshl_add_u64 v[132:133], s[14:15], 0, v[132:133]
	global_load_dwordx4 v[4:7], v[132:133], off
	s_waitcnt lgkmcnt(0)
	global_load_dwordx4 v[0:3], v[132:133], off offset:16
	v_lshlrev_b64 v[178:179], 10, v[138:139]
	v_lshl_add_u32 v129, v138, 2, 0
	v_lshlrev_b64 v[138:139], 10, v[140:141]
	v_lshl_add_u64 v[140:141], v[178:179], 0, v[130:131]
	ds_read_b32 v178, v129 offset:4096
	v_lshlrev_b64 v[134:135], 10, v[134:135]
	s_lshl_b64 s[4:5], s[22:23], 19
	v_lshl_add_u64 v[134:135], v[134:135], 0, v[130:131]
	v_lshl_add_u64 v[138:139], v[138:139], 0, v[130:131]
	v_lshlrev_b64 v[180:181], 1, v[140:141]
	s_add_u32 s4, s26, s4
	v_lshlrev_b64 v[182:183], 1, v[134:135]
	v_lshlrev_b64 v[184:185], 1, v[138:139]
	v_lshl_add_u64 v[140:141], s[2:3], 0, v[180:181]
	s_waitcnt lgkmcnt(0)
	v_pk_mul_f32 v[186:187], v[124:125], v[178:179] op_sel_hi:[1,0]
	v_pk_mul_f32 v[188:189], v[126:127], v[178:179] op_sel_hi:[1,0]
	v_pk_mul_f32 v[190:191], v[120:121], v[178:179] op_sel_hi:[1,0]
	v_pk_mul_f32 v[178:179], v[122:123], v[178:179] op_sel_hi:[1,0]
	s_addc_u32 s5, s27, s5
	v_cvt_pk_bf16_f32 v124, v124, v125
	v_cvt_pk_bf16_f32 v125, v126, v127
	v_cvt_pk_bf16_f32 v126, v120, v121
	v_cvt_pk_bf16_f32 v127, v122, v123
	v_lshl_add_u64 v[138:139], s[2:3], 0, v[182:183]
	v_lshl_add_u64 v[134:135], s[2:3], 0, v[184:185]
	global_store_dwordx4 v[140:141], v[124:127], off
	v_lshl_add_u64 v[122:123], s[4:5], 0, v[182:183]
	v_lshl_add_u64 v[120:121], s[4:5], 0, v[184:185]
	v_lshl_add_u64 v[124:125], s[4:5], 0, v[180:181]
	s_waitcnt vmcnt(0)
	v_pk_mul_f32 v[182:183], v[12:13], v[186:187]
	v_pk_mul_f32 v[178:179], v[10:11], v[178:179]
	v_pk_mul_f32 v[184:185], v[8:9], v[190:191]
	v_pk_add_f32 v[126:127], v[172:173], 1.0 op_sel_hi:[1,0]
	v_pk_add_f32 v[170:171], v[170:171], 1.0 op_sel_hi:[1,0]
	v_pk_add_f32 v[172:173], v[176:177], 1.0 op_sel_hi:[1,0]
	v_pk_add_f32 v[174:175], v[174:175], 1.0 op_sel_hi:[1,0]
	v_pk_mul_f32 v[180:181], v[14:15], v[188:189]
	v_pk_fma_f32 v[176:177], v[170:171], v[182:183], v[4:5]
	v_pk_fma_f32 v[182:183], v[172:173], v[178:179], v[2:3]
	v_pk_fma_f32 v[178:179], v[174:175], v[184:185], v[0:1]
	v_pk_fma_f32 v[180:181], v[126:127], v[180:181], v[6:7]
	v_cvt_pk_bf16_f32 v176, v176, v177
	s_nop 0
	v_cvt_pk_bf16_f32 v177, v180, v181
	v_cvt_pk_bf16_f32 v178, v178, v179
	v_cvt_pk_bf16_f32 v179, v182, v183
	global_store_dwordx4 v[124:125], v[176:179], off
	ds_read_b32 v180, v129 offset:4160
	s_nop 0
	v_cvt_pk_bf16_f32 v176, v108, v109
	v_cvt_pk_bf16_f32 v177, v110, v111
	v_cvt_pk_bf16_f32 v178, v104, v105
	v_cvt_pk_bf16_f32 v179, v106, v107
	s_waitcnt lgkmcnt(0)
	v_pk_mul_f32 v[104:105], v[104:105], v[180:181] op_sel_hi:[1,0]
	v_pk_mul_f32 v[106:107], v[106:107], v[180:181] op_sel_hi:[1,0]
	v_pk_mul_f32 v[108:109], v[108:109], v[180:181] op_sel_hi:[1,0]
	v_pk_mul_f32 v[110:111], v[110:111], v[180:181] op_sel_hi:[1,0]
	v_pk_mul_f32 v[106:107], v[10:11], v[106:107]
	v_pk_mul_f32 v[104:105], v[8:9], v[104:105]
	global_store_dwordx4 v[138:139], v[176:179], off
	v_pk_mul_f32 v[110:111], v[14:15], v[110:111]
	v_pk_mul_f32 v[108:109], v[12:13], v[108:109]
	v_pk_fma_f32 v[176:177], v[172:173], v[106:107], v[2:3]
	v_pk_fma_f32 v[106:107], v[174:175], v[104:105], v[0:1]
	v_pk_fma_f32 v[110:111], v[126:127], v[110:111], v[6:7]
	v_pk_fma_f32 v[108:109], v[170:171], v[108:109], v[4:5]
	s_nop 0
	v_cvt_pk_bf16_f32 v104, v108, v109
	v_cvt_pk_bf16_f32 v105, v110, v111
	v_cvt_pk_bf16_f32 v106, v106, v107
	v_cvt_pk_bf16_f32 v107, v176, v177
	global_store_dwordx4 v[122:123], v[104:107], off
	ds_read_b32 v108, v129 offset:4224
	s_nop 0
	v_cvt_pk_bf16_f32 v104, v92, v93
	v_cvt_pk_bf16_f32 v105, v94, v95
	v_cvt_pk_bf16_f32 v106, v88, v89
	v_cvt_pk_bf16_f32 v107, v90, v91
	s_waitcnt lgkmcnt(0)
	v_pk_mul_f32 v[88:89], v[88:89], v[108:109] op_sel_hi:[1,0]
	v_pk_mul_f32 v[90:91], v[90:91], v[108:109] op_sel_hi:[1,0]
	v_pk_mul_f32 v[92:93], v[92:93], v[108:109] op_sel_hi:[1,0]
	v_pk_mul_f32 v[94:95], v[94:95], v[108:109] op_sel_hi:[1,0]
	v_pk_mul_f32 v[90:91], v[10:11], v[90:91]
	v_pk_mul_f32 v[88:89], v[8:9], v[88:89]
	global_store_dwordx4 v[134:135], v[104:107], off
	v_pk_mul_f32 v[94:95], v[14:15], v[94:95]
	v_pk_mul_f32 v[92:93], v[12:13], v[92:93]
	v_pk_fma_f32 v[104:105], v[172:173], v[90:91], v[2:3]
	v_pk_fma_f32 v[90:91], v[174:175], v[88:89], v[0:1]
	v_pk_fma_f32 v[94:95], v[126:127], v[94:95], v[6:7]
	v_pk_fma_f32 v[92:93], v[170:171], v[92:93], v[4:5]
	s_nop 0
	v_cvt_pk_bf16_f32 v88, v92, v93
	v_cvt_pk_bf16_f32 v89, v94, v95
	v_cvt_pk_bf16_f32 v90, v90, v91
	v_cvt_pk_bf16_f32 v91, v104, v105
	global_store_dwordx4 v[120:121], v[88:91], off
	ds_read_b32 v88, v129 offset:4288
	s_waitcnt lgkmcnt(0)
; __device__ __forceinline__ unsigned cvt_pk_bf16(float lo, float hi) { unsigned r; asm volatile("v_cvt_pk_bf16_f32 %0, %1, %2" : "=v"(r) : "v"(lo), "v"(hi)); return r; }
;     __device__ __forceinline__ void fused(f32x4 (&acc)[2][2][4][2], const Unit& u, int wr, int wc, int fr, int fq, LAS unsigned char* lds, int tid) const {
;     ...
;                 for (int m = 0; m < 4; ++m) { const int r = ai * HALF + wr * 64 + m * 16 + fr; const size_t off = (size_t)r * DM + c; const float rs = S[r];
;                     const f32x4 x0 = acc[ai][bj][m][0], x1 = acc[ai][bj][m][1]; const f32x4 y0 = x0 * rs * g0, y1 = x1 * rs * g1;
;                     if (MODE == 0) { { u32x4 wx; wx.x = cvt_pk_bf16(x0[0], x0[1]); wx.y = cvt_pk_bf16(x0[2], x0[3]); wx.z = cvt_pk_bf16(x1[0], x1[1]); wx.w = cvt_pk_bf16(x1[2], x1[3]); *(u32x4*)(xb_ + off) = wx; }
;                         const f32x4 z0 = y0 * sc0 + sh0, z1 = y1 * sc1 + sh1;
;                         u32x4 w; w.x = cvt_pk_bf16(z0[0], z0[1]); w.y = cvt_pk_bf16(z0[2], z0[3]); w.z = cvt_pk_bf16(z1[0], z1[1]); w.w = cvt_pk_bf16(z1[2], z1[3]);
;                         *(u32x4*)(XN + (size_t)u.pm * BM * DM + off) = w; }
;                     else { *(f32x4*)(out_ + off) = y0; *(f32x4*)(out_ + off + 4) = y1; } }
;             asm volatile("" ::: "memory"); }
	v_pk_mul_f32 v[92:93], v[76:77], v[88:89] op_sel_hi:[1,0]
	v_lshlrev_b64 v[90:91], 10, v[136:137]
	v_lshl_add_u64 v[90:91], v[90:91], 0, v[130:131]
	v_pk_mul_f32 v[94:95], v[78:79], v[88:89] op_sel_hi:[1,0]
	v_pk_mul_f32 v[104:105], v[72:73], v[88:89] op_sel_hi:[1,0]
	v_pk_mul_f32 v[88:89], v[74:75], v[88:89] op_sel_hi:[1,0]
	v_cvt_pk_bf16_f32 v76, v76, v77
	v_cvt_pk_bf16_f32 v77, v78, v79
	v_cvt_pk_bf16_f32 v78, v72, v73
	v_cvt_pk_bf16_f32 v79, v74, v75
	v_lshlrev_b64 v[74:75], 1, v[90:91]
	v_pk_mul_f32 v[94:95], v[14:15], v[94:95]
	v_pk_mul_f32 v[92:93], v[12:13], v[92:93]
	v_lshl_add_u64 v[72:73], s[2:3], 0, v[74:75]
	v_pk_mul_f32 v[88:89], v[10:11], v[88:89]
	v_pk_mul_f32 v[104:105], v[8:9], v[104:105]
	global_store_dwordx4 v[72:73], v[76:79], off
	v_lshl_add_u64 v[74:75], s[4:5], 0, v[74:75]
	v_pk_fma_f32 v[88:89], v[172:173], v[88:89], v[2:3]
	v_pk_fma_f32 v[78:79], v[126:127], v[94:95], v[6:7]
	v_pk_fma_f32 v[76:77], v[170:171], v[92:93], v[4:5]
	v_pk_fma_f32 v[90:91], v[174:175], v[104:105], v[0:1]
	v_cvt_pk_bf16_f32 v76, v76, v77
	v_cvt_pk_bf16_f32 v77, v78, v79
	s_nop 0
	v_cvt_pk_bf16_f32 v78, v90, v91
	v_cvt_pk_bf16_f32 v79, v88, v89
	global_store_dwordx4 v[74:75], v[76:79], off
	ds_read_b32 v76, v129 offset:4608
	s_waitcnt lgkmcnt(0)
	v_pk_mul_f32 v[88:89], v[60:61], v[76:77] op_sel_hi:[1,0]
	v_lshlrev_b64 v[78:79], 10, v[142:143]
	v_lshl_add_u64 v[78:79], v[78:79], 0, v[130:131]
	v_pk_mul_f32 v[90:91], v[62:63], v[76:77] op_sel_hi:[1,0]
	v_pk_mul_f32 v[92:93], v[56:57], v[76:77] op_sel_hi:[1,0]
	v_pk_mul_f32 v[76:77], v[58:59], v[76:77] op_sel_hi:[1,0]
	v_cvt_pk_bf16_f32 v60, v60, v61
	v_cvt_pk_bf16_f32 v61, v62, v63
	v_cvt_pk_bf16_f32 v62, v56, v57
	v_cvt_pk_bf16_f32 v63, v58, v59
	v_lshlrev_b64 v[58:59], 1, v[78:79]
	v_pk_mul_f32 v[90:91], v[14:15], v[90:91]
	v_pk_mul_f32 v[88:89], v[12:13], v[88:89]
	v_lshl_add_u64 v[56:57], s[2:3], 0, v[58:59]
	v_pk_mul_f32 v[76:77], v[10:11], v[76:77]
	v_pk_mul_f32 v[92:93], v[8:9], v[92:93]
	global_store_dwordx4 v[56:57], v[60:63], off
	v_lshl_add_u64 v[58:59], s[4:5], 0, v[58:59]
	v_pk_fma_f32 v[76:77], v[172:173], v[76:77], v[2:3]
	v_pk_fma_f32 v[62:63], v[126:127], v[90:91], v[6:7]
	v_pk_fma_f32 v[60:61], v[170:171], v[88:89], v[4:5]
	v_pk_fma_f32 v[78:79], v[174:175], v[92:93], v[0:1]
	v_cvt_pk_bf16_f32 v60, v60, v61
	v_cvt_pk_bf16_f32 v61, v62, v63
	s_nop 0
	v_cvt_pk_bf16_f32 v62, v78, v79
	v_cvt_pk_bf16_f32 v63, v76, v77
	global_store_dwordx4 v[58:59], v[60:63], off
	ds_read_b32 v60, v129 offset:4672
	s_waitcnt lgkmcnt(0)
	v_pk_mul_f32 v[76:77], v[44:45], v[60:61] op_sel_hi:[1,0]
	v_lshlrev_b64 v[62:63], 10, v[144:145]
	v_lshl_add_u64 v[62:63], v[62:63], 0, v[130:131]
	v_pk_mul_f32 v[78:79], v[46:47], v[60:61] op_sel_hi:[1,0]
	v_pk_mul_f32 v[88:89], v[40:41], v[60:61] op_sel_hi:[1,0]
	v_pk_mul_f32 v[60:61], v[42:43], v[60:61] op_sel_hi:[1,0]
	v_cvt_pk_bf16_f32 v44, v44, v45
	v_cvt_pk_bf16_f32 v45, v46, v47
	v_cvt_pk_bf16_f32 v46, v40, v41
	v_cvt_pk_bf16_f32 v47, v42, v43
	v_lshlrev_b64 v[42:43], 1, v[62:63]
	v_pk_mul_f32 v[78:79], v[14:15], v[78:79]
	v_pk_mul_f32 v[76:77], v[12:13], v[76:77]
	v_lshl_add_u64 v[40:41], s[2:3], 0, v[42:43]
	v_pk_mul_f32 v[60:61], v[10:11], v[60:61]
	v_pk_mul_f32 v[88:89], v[8:9], v[88:89]
	global_store_dwordx4 v[40:41], v[44:47], off
	v_lshl_add_u64 v[42:43], s[4:5], 0, v[42:43]
	v_pk_fma_f32 v[60:61], v[172:173], v[60:61], v[2:3]
	v_pk_fma_f32 v[46:47], v[126:127], v[78:79], v[6:7]
	v_pk_fma_f32 v[44:45], v[170:171], v[76:77], v[4:5]
	v_pk_fma_f32 v[62:63], v[174:175], v[88:89], v[0:1]
	v_cvt_pk_bf16_f32 v44, v44, v45
	v_cvt_pk_bf16_f32 v45, v46, v47
	s_nop 0
	v_cvt_pk_bf16_f32 v46, v62, v63
	v_cvt_pk_bf16_f32 v47, v60, v61
	global_store_dwordx4 v[42:43], v[44:47], off
	ds_read_b32 v44, v129 offset:4736
	s_waitcnt lgkmcnt(0)
	v_pk_mul_f32 v[60:61], v[154:155], v[44:45] op_sel_hi:[1,0]
	v_lshlrev_b64 v[46:47], 10, v[146:147]
	v_lshl_add_u64 v[46:47], v[46:47], 0, v[130:131]
	v_pk_mul_f32 v[62:63], v[150:151], v[44:45] op_sel_hi:[1,0]
	v_pk_mul_f32 v[78:79], v[12:13], v[60:61]
	v_pk_mul_f32 v[60:61], v[152:153], v[44:45] op_sel_hi:[1,0]
	v_pk_mul_f32 v[44:45], v[148:149], v[44:45] op_sel_hi:[1,0]
	v_lshlrev_b64 v[46:47], 1, v[46:47]
	v_pk_mul_f32 v[76:77], v[14:15], v[62:63]
	v_pk_mul_f32 v[88:89], v[10:11], v[44:45]
	v_pk_mul_f32 v[90:91], v[8:9], v[60:61]
	v_cvt_pk_bf16_f32 v60, v154, v155
	v_cvt_pk_bf16_f32 v61, v150, v151
	v_cvt_pk_bf16_f32 v62, v152, v153
	v_cvt_pk_bf16_f32 v63, v148, v149
	v_lshl_add_u64 v[44:45], s[2:3], 0, v[46:47]
	global_store_dwordx4 v[44:45], v[60:63], off
	v_lshl_add_u64 v[46:47], s[4:5], 0, v[46:47]
	s_nop 0
	v_pk_fma_f32 v[62:63], v[126:127], v[76:77], v[6:7]
	v_pk_fma_f32 v[60:61], v[170:171], v[78:79], v[4:5]
	v_pk_fma_f32 v[76:77], v[172:173], v[88:89], v[2:3]
	v_pk_fma_f32 v[78:79], v[174:175], v[90:91], v[0:1]
	v_cvt_pk_bf16_f32 v60, v60, v61
	v_cvt_pk_bf16_f32 v61, v62, v63
	s_nop 0
	v_cvt_pk_bf16_f32 v62, v78, v79
	v_cvt_pk_bf16_f32 v63, v76, v77
	global_store_dwordx4 v[46:47], v[60:63], off
	ds_read_b32 v60, v129 offset:4800
	s_waitcnt lgkmcnt(0)
; __device__ __forceinline__ unsigned cvt_pk_bf16(float lo, float hi) { unsigned r; asm volatile("v_cvt_pk_bf16_f32 %0, %1, %2" : "=v"(r) : "v"(lo), "v"(hi)); return r; }
;     __device__ __forceinline__ void fused(f32x4 (&acc)[2][2][4][2], const Unit& u, int wr, int wc, int fr, int fq, LAS unsigned char* lds, int tid) const {
;     ...
;         for (int bj = 0; bj < 2; ++bj) { const int c = col0 + bj * HALF;
;             const f32x4 g0 = *(const f32x4*)(g + c), g1 = *(const f32x4*)(g + c + 4);
;             f32x4 sc0 = {0.f, 0.f, 0.f, 0.f}, sc1 = sc0, sh0 = sc0, sh1 = sc0;
;             if (MODE == 0) { sc0 = *(const f32x4*)(scale + (size_t)cls * MODLD + c) + 1.0f; sc1 = *(const f32x4*)(scale + (size_t)cls * MODLD + c + 4) + 1.0f;
;                 sh0 = *(const f32x4*)(shift + (size_t)cls * MODLD + c); sh1 = *(const f32x4*)(shift + (size_t)cls * MODLD + c + 4); }
; #pragma unroll
;             for (int ai = 0; ai < 2; ++ai)
; #pragma unroll
;                 for (int m = 0; m < 4; ++m) { const int r = ai * HALF + wr * 64 + m * 16 + fr; const size_t off = (size_t)r * DM + c; const float rs = S[r];
;                     const f32x4 x0 = acc[ai][bj][m][0], x1 = acc[ai][bj][m][1]; const f32x4 y0 = x0 * rs * g0, y1 = x1 * rs * g1;
;                     if (MODE == 0) { { u32x4 wx; wx.x = cvt_pk_bf16(x0[0], x0[1]); wx.y = cvt_pk_bf16(x0[2], x0[3]); wx.z = cvt_pk_bf16(x1[0], x1[1]); wx.w = cvt_pk_bf16(x1[2], x1[3]); *(u32x4*)(xb_ + off) = wx; }
;                         const f32x4 z0 = y0 * sc0 + sh0, z1 = y1 * sc1 + sh1;
;                         u32x4 w; w.x = cvt_pk_bf16(z0[0], z0[1]); w.y = cvt_pk_bf16(z0[2], z0[3]); w.z = cvt_pk_bf16(z1[0], z1[1]); w.w = cvt_pk_bf16(z1[2], z1[3]);
;                         *(u32x4*)(XN + (size_t)u.pm * BM * DM + off) = w; }
;                     else { *(f32x4*)(out_ + off) = y0; *(f32x4*)(out_ + off + 4) = y1; } }
;             asm volatile("" ::: "memory"); }
	v_pk_mul_f32 v[76:77], v[164:165], v[60:61] op_sel_hi:[1,0]
	v_lshlrev_b64 v[62:63], 10, v[156:157]
	v_lshl_add_u64 v[62:63], v[62:63], 0, v[130:131]
	v_pk_mul_f32 v[78:79], v[160:161], v[60:61] op_sel_hi:[1,0]
	v_pk_mul_f32 v[12:13], v[12:13], v[76:77]
	v_pk_mul_f32 v[76:77], v[162:163], v[60:61] op_sel_hi:[1,0]
	v_pk_mul_f32 v[60:61], v[158:159], v[60:61] op_sel_hi:[1,0]
	v_lshlrev_b64 v[62:63], 1, v[62:63]
	v_pk_mul_f32 v[14:15], v[14:15], v[78:79]
	v_pk_mul_f32 v[78:79], v[10:11], v[60:61]
	v_pk_mul_f32 v[76:77], v[8:9], v[76:77]
	v_cvt_pk_bf16_f32 v8, v164, v165
	v_cvt_pk_bf16_f32 v9, v160, v161
	v_lshl_add_u64 v[60:61], s[2:3], 0, v[62:63]
	v_cvt_pk_bf16_f32 v10, v162, v163
	v_cvt_pk_bf16_f32 v11, v158, v159
	global_store_dwordx4 v[60:61], v[8:11], off
	v_lshl_add_u64 v[62:63], s[4:5], 0, v[62:63]
	v_pk_fma_f32 v[6:7], v[126:127], v[14:15], v[6:7]
	v_pk_fma_f32 v[8:9], v[172:173], v[78:79], v[2:3]
	v_pk_fma_f32 v[2:3], v[174:175], v[76:77], v[0:1]
	v_pk_fma_f32 v[4:5], v[170:171], v[12:13], v[4:5]
	s_nop 0
	v_cvt_pk_bf16_f32 v0, v4, v5
	v_cvt_pk_bf16_f32 v1, v6, v7
	v_cvt_pk_bf16_f32 v2, v2, v3
	v_cvt_pk_bf16_f32 v3, v8, v9
	global_store_dwordx4 v[62:63], v[0:3], off
	global_load_dwordx4 v[88:91], v[168:169], off offset:512
	global_load_dwordx4 v[92:95], v[168:169], off offset:528
	global_load_dwordx4 v[12:15], v[166:167], off offset:512
	global_load_dwordx4 v[8:11], v[166:167], off offset:528
	global_load_dwordx4 v[4:7], v[132:133], off offset:512
	global_load_dwordx4 v[0:3], v[132:133], off offset:528
	ds_read_b32 v104, v129 offset:4096
	s_waitcnt vmcnt(0) lgkmcnt(0)
	v_pk_add_f32 v[76:77], v[90:91], 1.0 op_sel_hi:[1,0]
	v_pk_add_f32 v[78:79], v[88:89], 1.0 op_sel_hi:[1,0]
	v_pk_add_f32 v[88:89], v[94:95], 1.0 op_sel_hi:[1,0]
	v_pk_add_f32 v[90:91], v[92:93], 1.0 op_sel_hi:[1,0]
	v_pk_mul_f32 v[92:93], v[116:117], v[104:105] op_sel_hi:[1,0]
	v_pk_mul_f32 v[94:95], v[118:119], v[104:105] op_sel_hi:[1,0]
	v_pk_mul_f32 v[108:109], v[12:13], v[92:93]
	v_pk_mul_f32 v[106:107], v[14:15], v[94:95]
	v_pk_mul_f32 v[92:93], v[112:113], v[104:105] op_sel_hi:[1,0]
	v_pk_mul_f32 v[94:95], v[114:115], v[104:105] op_sel_hi:[1,0]
	v_pk_mul_f32 v[110:111], v[8:9], v[92:93]
	v_pk_mul_f32 v[104:105], v[10:11], v[94:95]
	v_cvt_pk_bf16_f32 v92, v116, v117
	v_cvt_pk_bf16_f32 v93, v118, v119
	v_cvt_pk_bf16_f32 v94, v112, v113
	v_cvt_pk_bf16_f32 v95, v114, v115
	global_store_dwordx4 v[140:141], v[92:95], off offset:256
	v_pk_fma_f32 v[104:105], v[88:89], v[104:105], v[2:3]
	s_nop 0
	v_pk_fma_f32 v[94:95], v[76:77], v[106:107], v[6:7]
	v_pk_fma_f32 v[92:93], v[78:79], v[108:109], v[4:5]
	v_pk_fma_f32 v[106:107], v[90:91], v[110:111], v[0:1]
	v_cvt_pk_bf16_f32 v92, v92, v93
	v_cvt_pk_bf16_f32 v93, v94, v95
	s_nop 0
	v_cvt_pk_bf16_f32 v94, v106, v107
	v_cvt_pk_bf16_f32 v95, v104, v105
	global_store_dwordx4 v[124:125], v[92:95], off offset:256
	ds_read_b32 v92, v129 offset:4160
	s_waitcnt lgkmcnt(0)
	v_pk_mul_f32 v[104:105], v[102:103], v[92:93] op_sel_hi:[1,0]
	v_pk_mul_f32 v[94:95], v[100:101], v[92:93] op_sel_hi:[1,0]
	v_pk_mul_f32 v[104:105], v[14:15], v[104:105]
	v_pk_mul_f32 v[106:107], v[12:13], v[94:95]
	v_pk_mul_f32 v[94:95], v[96:97], v[92:93] op_sel_hi:[1,0]
	v_pk_mul_f32 v[92:93], v[98:99], v[92:93] op_sel_hi:[1,0]
	v_pk_mul_f32 v[110:111], v[8:9], v[94:95]
	v_pk_mul_f32 v[108:109], v[10:11], v[92:93]
	v_cvt_pk_bf16_f32 v92, v100, v101
	v_cvt_pk_bf16_f32 v93, v102, v103
	v_cvt_pk_bf16_f32 v94, v96, v97
	v_cvt_pk_bf16_f32 v95, v98, v99
	global_store_dwordx4 v[138:139], v[92:95], off offset:256
	v_pk_fma_f32 v[96:97], v[88:89], v[108:109], v[2:3]
	v_pk_fma_f32 v[98:99], v[90:91], v[110:111], v[0:1]
	v_pk_fma_f32 v[94:95], v[76:77], v[104:105], v[6:7]
	v_pk_fma_f32 v[92:93], v[78:79], v[106:107], v[4:5]
	s_nop 0
	v_cvt_pk_bf16_f32 v92, v92, v93
	v_cvt_pk_bf16_f32 v93, v94, v95
	v_cvt_pk_bf16_f32 v94, v98, v99
	v_cvt_pk_bf16_f32 v95, v96, v97
	global_store_dwordx4 v[122:123], v[92:95], off offset:256
	ds_read_b32 v92, v129 offset:4224
	s_waitcnt lgkmcnt(0)
	v_pk_mul_f32 v[96:97], v[86:87], v[92:93] op_sel_hi:[1,0]
	v_pk_mul_f32 v[94:95], v[84:85], v[92:93] op_sel_hi:[1,0]
	v_pk_mul_f32 v[96:97], v[14:15], v[96:97]
	v_pk_mul_f32 v[94:95], v[12:13], v[94:95]
	v_pk_mul_f32 v[98:99], v[80:81], v[92:93] op_sel_hi:[1,0]
	v_pk_mul_f32 v[92:93], v[82:83], v[92:93] op_sel_hi:[1,0]
	v_pk_mul_f32 v[98:99], v[8:9], v[98:99]
	v_pk_mul_f32 v[92:93], v[10:11], v[92:93]
	v_cvt_pk_bf16_f32 v84, v84, v85
	v_cvt_pk_bf16_f32 v85, v86, v87
	v_cvt_pk_bf16_f32 v86, v80, v81
	v_cvt_pk_bf16_f32 v87, v82, v83
	v_pk_fma_f32 v[82:83], v[76:77], v[96:97], v[6:7]
	v_pk_fma_f32 v[80:81], v[78:79], v[94:95], v[4:5]
	global_store_dwordx4 v[134:135], v[84:87], off offset:256
	v_cvt_pk_bf16_f32 v80, v80, v81
	v_cvt_pk_bf16_f32 v81, v82, v83
	s_nop 1
	v_pk_fma_f32 v[84:85], v[88:89], v[92:93], v[2:3]
	v_pk_fma_f32 v[86:87], v[90:91], v[98:99], v[0:1]
	s_nop 0
	v_cvt_pk_bf16_f32 v82, v86, v87
	v_cvt_pk_bf16_f32 v83, v84, v85
	global_store_dwordx4 v[120:121], v[80:83], off offset:256
	ds_read_b32 v80, v129 offset:4288
	s_waitcnt lgkmcnt(0)
; __device__ __forceinline__ unsigned cvt_pk_bf16(float lo, float hi) { unsigned r; asm volatile("v_cvt_pk_bf16_f32 %0, %1, %2" : "=v"(r) : "v"(lo), "v"(hi)); return r; }
;     __device__ __forceinline__ void fused(f32x4 (&acc)[2][2][4][2], const Unit& u, int wr, int wc, int fr, int fq, LAS unsigned char* lds, int tid) const {
;     ...
;                 for (int m = 0; m < 4; ++m) { const int r = ai * HALF + wr * 64 + m * 16 + fr; const size_t off = (size_t)r * DM + c; const float rs = S[r];
;                     const f32x4 x0 = acc[ai][bj][m][0], x1 = acc[ai][bj][m][1]; const f32x4 y0 = x0 * rs * g0, y1 = x1 * rs * g1;
;                     if (MODE == 0) { { u32x4 wx; wx.x = cvt_pk_bf16(x0[0], x0[1]); wx.y = cvt_pk_bf16(x0[2], x0[3]); wx.z = cvt_pk_bf16(x1[0], x1[1]); wx.w = cvt_pk_bf16(x1[2], x1[3]); *(u32x4*)(xb_ + off) = wx; }
;                         const f32x4 z0 = y0 * sc0 + sh0, z1 = y1 * sc1 + sh1;
;                         u32x4 w; w.x = cvt_pk_bf16(z0[0], z0[1]); w.y = cvt_pk_bf16(z0[2], z0[3]); w.z = cvt_pk_bf16(z1[0], z1[1]); w.w = cvt_pk_bf16(z1[2], z1[3]);
;                         *(u32x4*)(XN + (size_t)u.pm * BM * DM + off) = w; }
;                     else { *(f32x4*)(out_ + off) = y0; *(f32x4*)(out_ + off + 4) = y1; } }
;             asm volatile("" ::: "memory"); }
;         asm volatile("s_waitcnt lgkmcnt(0)" ::: "memory"); __builtin_amdgcn_s_barrier(); asm volatile("" ::: "memory");
	v_pk_mul_f32 v[84:85], v[70:71], v[80:81] op_sel_hi:[1,0]
	v_pk_mul_f32 v[82:83], v[68:69], v[80:81] op_sel_hi:[1,0]
	v_pk_mul_f32 v[84:85], v[14:15], v[84:85]
	v_pk_mul_f32 v[82:83], v[12:13], v[82:83]
	v_pk_mul_f32 v[86:87], v[64:65], v[80:81] op_sel_hi:[1,0]
	v_pk_mul_f32 v[80:81], v[66:67], v[80:81] op_sel_hi:[1,0]
	v_pk_mul_f32 v[86:87], v[8:9], v[86:87]
	v_pk_mul_f32 v[80:81], v[10:11], v[80:81]
	v_cvt_pk_bf16_f32 v68, v68, v69
	v_cvt_pk_bf16_f32 v69, v70, v71
	v_cvt_pk_bf16_f32 v70, v64, v65
	v_cvt_pk_bf16_f32 v71, v66, v67
	v_pk_fma_f32 v[66:67], v[76:77], v[84:85], v[6:7]
	v_pk_fma_f32 v[64:65], v[78:79], v[82:83], v[4:5]
	global_store_dwordx4 v[72:73], v[68:71], off offset:256
	v_cvt_pk_bf16_f32 v64, v64, v65
	v_cvt_pk_bf16_f32 v65, v66, v67
	s_nop 1
	v_pk_fma_f32 v[68:69], v[88:89], v[80:81], v[2:3]
	v_pk_fma_f32 v[70:71], v[90:91], v[86:87], v[0:1]
	s_nop 0
	v_cvt_pk_bf16_f32 v66, v70, v71
	v_cvt_pk_bf16_f32 v67, v68, v69
	global_store_dwordx4 v[74:75], v[64:67], off offset:256
	ds_read_b32 v64, v129 offset:4608
	s_waitcnt lgkmcnt(0)
	v_pk_mul_f32 v[68:69], v[54:55], v[64:65] op_sel_hi:[1,0]
	v_pk_mul_f32 v[66:67], v[52:53], v[64:65] op_sel_hi:[1,0]
	v_pk_mul_f32 v[68:69], v[14:15], v[68:69]
	v_pk_mul_f32 v[66:67], v[12:13], v[66:67]
	v_pk_mul_f32 v[70:71], v[48:49], v[64:65] op_sel_hi:[1,0]
	v_pk_mul_f32 v[64:65], v[50:51], v[64:65] op_sel_hi:[1,0]
	v_pk_mul_f32 v[70:71], v[8:9], v[70:71]
	v_pk_mul_f32 v[64:65], v[10:11], v[64:65]
	v_cvt_pk_bf16_f32 v52, v52, v53
	v_cvt_pk_bf16_f32 v53, v54, v55
	v_cvt_pk_bf16_f32 v54, v48, v49
	v_cvt_pk_bf16_f32 v55, v50, v51
	v_pk_fma_f32 v[50:51], v[76:77], v[68:69], v[6:7]
	v_pk_fma_f32 v[48:49], v[78:79], v[66:67], v[4:5]
	global_store_dwordx4 v[56:57], v[52:55], off offset:256
	v_cvt_pk_bf16_f32 v48, v48, v49
	v_cvt_pk_bf16_f32 v49, v50, v51
	s_nop 1
	v_pk_fma_f32 v[52:53], v[88:89], v[64:65], v[2:3]
	v_pk_fma_f32 v[54:55], v[90:91], v[70:71], v[0:1]
	s_nop 0
	v_cvt_pk_bf16_f32 v50, v54, v55
	v_cvt_pk_bf16_f32 v51, v52, v53
	global_store_dwordx4 v[58:59], v[48:51], off offset:256
	ds_read_b32 v48, v129 offset:4672
	s_waitcnt lgkmcnt(0)
	v_pk_mul_f32 v[52:53], v[38:39], v[48:49] op_sel_hi:[1,0]
	v_pk_mul_f32 v[50:51], v[36:37], v[48:49] op_sel_hi:[1,0]
	v_pk_mul_f32 v[52:53], v[14:15], v[52:53]
	v_pk_mul_f32 v[50:51], v[12:13], v[50:51]
	v_pk_mul_f32 v[54:55], v[32:33], v[48:49] op_sel_hi:[1,0]
	v_pk_mul_f32 v[48:49], v[34:35], v[48:49] op_sel_hi:[1,0]
	v_pk_mul_f32 v[54:55], v[8:9], v[54:55]
	v_pk_mul_f32 v[48:49], v[10:11], v[48:49]
	v_cvt_pk_bf16_f32 v36, v36, v37
	v_cvt_pk_bf16_f32 v37, v38, v39
	v_cvt_pk_bf16_f32 v38, v32, v33
	v_cvt_pk_bf16_f32 v39, v34, v35
	v_pk_fma_f32 v[34:35], v[76:77], v[52:53], v[6:7]
	v_pk_fma_f32 v[32:33], v[78:79], v[50:51], v[4:5]
	global_store_dwordx4 v[40:41], v[36:39], off offset:256
	v_cvt_pk_bf16_f32 v32, v32, v33
	v_cvt_pk_bf16_f32 v33, v34, v35
	s_nop 1
	v_pk_fma_f32 v[36:37], v[88:89], v[48:49], v[2:3]
	v_pk_fma_f32 v[38:39], v[90:91], v[54:55], v[0:1]
	s_nop 0
	v_cvt_pk_bf16_f32 v34, v38, v39
	v_cvt_pk_bf16_f32 v35, v36, v37
	global_store_dwordx4 v[42:43], v[32:35], off offset:256
	ds_read_b32 v32, v129 offset:4736
	s_waitcnt lgkmcnt(0)
	v_pk_mul_f32 v[36:37], v[22:23], v[32:33] op_sel_hi:[1,0]
	v_pk_mul_f32 v[34:35], v[20:21], v[32:33] op_sel_hi:[1,0]
	v_pk_mul_f32 v[36:37], v[14:15], v[36:37]
	v_pk_mul_f32 v[34:35], v[12:13], v[34:35]
	v_pk_mul_f32 v[38:39], v[16:17], v[32:33] op_sel_hi:[1,0]
	v_pk_mul_f32 v[32:33], v[18:19], v[32:33] op_sel_hi:[1,0]
	v_pk_mul_f32 v[38:39], v[8:9], v[38:39]
	v_pk_mul_f32 v[32:33], v[10:11], v[32:33]
	v_cvt_pk_bf16_f32 v20, v20, v21
	v_cvt_pk_bf16_f32 v21, v22, v23
	v_cvt_pk_bf16_f32 v22, v16, v17
	v_cvt_pk_bf16_f32 v23, v18, v19
	v_pk_fma_f32 v[18:19], v[76:77], v[36:37], v[6:7]
	v_pk_fma_f32 v[16:17], v[78:79], v[34:35], v[4:5]
	global_store_dwordx4 v[44:45], v[20:23], off offset:256
	v_cvt_pk_bf16_f32 v16, v16, v17
	v_cvt_pk_bf16_f32 v17, v18, v19
	s_nop 1
	v_pk_fma_f32 v[20:21], v[88:89], v[32:33], v[2:3]
	v_pk_fma_f32 v[22:23], v[90:91], v[38:39], v[0:1]
	s_nop 0
	v_cvt_pk_bf16_f32 v18, v22, v23
	v_cvt_pk_bf16_f32 v19, v20, v21
	global_store_dwordx4 v[46:47], v[16:19], off offset:256
	ds_read_b32 v16, v129 offset:4800
	s_waitcnt lgkmcnt(0)
	v_pk_mul_f32 v[20:21], v[24:25], v[16:17] op_sel_hi:[1,0]
	v_pk_mul_f32 v[18:19], v[28:29], v[16:17] op_sel_hi:[1,0]
	v_pk_mul_f32 v[14:15], v[14:15], v[20:21]
	v_pk_mul_f32 v[12:13], v[12:13], v[18:19]
	v_pk_mul_f32 v[18:19], v[30:31], v[16:17] op_sel_hi:[1,0]
	v_pk_mul_f32 v[16:17], v[26:27], v[16:17] op_sel_hi:[1,0]
	v_pk_mul_f32 v[18:19], v[8:9], v[18:19]
	v_pk_mul_f32 v[16:17], v[10:11], v[16:17]
	v_cvt_pk_bf16_f32 v8, v28, v29
	v_cvt_pk_bf16_f32 v9, v24, v25
	v_cvt_pk_bf16_f32 v10, v30, v31
	v_cvt_pk_bf16_f32 v11, v26, v27
	global_store_dwordx4 v[60:61], v[8:11], off offset:256
	v_pk_fma_f32 v[6:7], v[76:77], v[14:15], v[6:7]
	v_pk_fma_f32 v[4:5], v[78:79], v[12:13], v[4:5]
	v_pk_fma_f32 v[8:9], v[88:89], v[16:17], v[2:3]
	v_pk_fma_f32 v[2:3], v[90:91], v[18:19], v[0:1]
	v_cvt_pk_bf16_f32 v0, v4, v5
	v_cvt_pk_bf16_f32 v1, v6, v7
	s_nop 0
	v_cvt_pk_bf16_f32 v2, v2, v3
	v_cvt_pk_bf16_f32 v3, v8, v9
	global_store_dwordx4 v[62:63], v[0:3], off offset:256
	s_waitcnt lgkmcnt(0)
	s_barrier

; __device__ __forceinline__ unsigned cvt_pk_bf16(float lo, float hi) { unsigned r; asm volatile("v_cvt_pk_bf16_f32 %0, %1, %2" : "=v"(r) : "v"(lo), "v"(hi)); return r; }
;     __device__ __forceinline__ void fused(f32x4 (&acc)[2][2][4][2], const Unit& u, int wr, int wc, int fr, int fq, LAS unsigned char* lds, int tid) const {
;     ...
;         for (int bj = 0; bj < 2; ++bj) { const int c = col0 + bj * HALF;
;             const f32x4 g0 = *(const f32x4*)(g + c), g1 = *(const f32x4*)(g + c + 4);
;             f32x4 sc0 = {0.f, 0.f, 0.f, 0.f}, sc1 = sc0, sh0 = sc0, sh1 = sc0;
;             if (MODE == 0) { sc0 = *(const f32x4*)(scale + (size_t)cls * MODLD + c) + 1.0f; sc1 = *(const f32x4*)(scale + (size_t)cls * MODLD + c + 4) + 1.0f;
;                 sh0 = *(const f32x4*)(shift + (size_t)cls * MODLD + c); sh1 = *(const f32x4*)(shift + (size_t)cls * MODLD + c + 4); }
; #pragma unroll
;             for (int ai = 0; ai < 2; ++ai)
; #pragma unroll
;                 for (int m = 0; m < 4; ++m) { const int r = ai * HALF + wr * 64 + m * 16 + fr; const size_t off = (size_t)r * DM + c; const float rs = S[r];
;                     const f32x4 x0 = acc[ai][bj][m][0], x1 = acc[ai][bj][m][1]; const f32x4 y0 = x0 * rs * g0, y1 = x1 * rs * g1;
;                     if (MODE == 0) { { u32x4 wx; wx.x = cvt_pk_bf16(x0[0], x0[1]); wx.y = cvt_pk_bf16(x0[2], x0[3]); wx.z = cvt_pk_bf16(x1[0], x1[1]); wx.w = cvt_pk_bf16(x1[2], x1[3]); *(u32x4*)(xb_ + off) = wx; }
;                         const f32x4 z0 = y0 * sc0 + sh0, z1 = y1 * sc1 + sh1;
;                         u32x4 w; w.x = cvt_pk_bf16(z0[0], z0[1]); w.y = cvt_pk_bf16(z0[2], z0[3]); w.z = cvt_pk_bf16(z1[0], z1[1]); w.w = cvt_pk_bf16(z1[2], z1[3]);
;                         *(u32x4*)(XN + (size_t)u.pm * BM * DM + off) = w; }
;                     else { *(f32x4*)(out_ + off) = y0; *(f32x4*)(out_ + off + 4) = y1; } }
;             asm volatile("" ::: "memory"); }
.LBB0_1151:
	s_or_b64 exec, exec, s[2:3]
	s_add_u32 s0, s24, s13
	s_addc_u32 s1, s25, s12
	s_waitcnt lgkmcnt(0)
	v_lshlrev_b64 v[0:1], 2, v[132:133]
	s_waitcnt lgkmcnt(0)
	s_barrier
	v_lshl_add_u64 v[144:145], s[26:27], 0, v[0:1]
	s_add_u32 s2, s22, s13
	v_lshl_add_u64 v[180:181], s[0:1], 0, v[0:1]
	global_load_dwordx4 v[12:15], v[144:145], off
	global_load_dwordx4 v[8:11], v[144:145], off offset:16
	global_load_dwordx4 v[186:189], v[180:181], off
	global_load_dwordx4 v[190:193], v[180:181], off offset:16
	s_addc_u32 s3, s23, s12
	v_lshl_add_u64 v[182:183], s[2:3], 0, v[0:1]
	global_load_dwordx4 v[4:7], v[182:183], off
	global_load_dwordx4 v[0:3], v[182:183], off offset:16
	v_lshl_add_u32 v184, v128, 2, 0
	ds_read_b32 v198, v184 offset:4096
	v_lshlrev_b64 v[194:195], 10, v[128:129]
	v_lshlrev_b64 v[128:129], 10, v[138:139]
	s_add_u32 s0, s8, s10
	v_lshlrev_b64 v[138:139], 10, v[146:147]
	v_lshl_add_u64 v[146:147], v[194:195], 0, v[132:133]
	v_lshl_add_u64 v[128:129], v[128:129], 0, v[132:133]
	s_addc_u32 s1, s9, s11
	v_cvt_pk_bf16_f32 v194, v134, v135
	v_cvt_pk_bf16_f32 v195, v126, v127
	v_cvt_pk_bf16_f32 v196, v124, v125
	v_cvt_pk_bf16_f32 v197, v122, v123
	s_waitcnt lgkmcnt(0)
	v_pk_mul_f32 v[134:135], v[134:135], v[198:199] op_sel_hi:[1,0]
	v_pk_mul_f32 v[202:203], v[126:127], v[198:199] op_sel_hi:[1,0]
	v_lshl_add_u64 v[138:139], v[138:139], 0, v[132:133]
	v_pk_mul_f32 v[204:205], v[124:125], v[198:199] op_sel_hi:[1,0]
	v_pk_mul_f32 v[198:199], v[122:123], v[198:199] op_sel_hi:[1,0]
	global_store_dwordx4 v[130:131], v[194:197], off
	v_lshl_add_u64 v[122:123], v[128:129], 1, s[0:1]
	v_lshl_add_u64 v[126:127], v[146:147], 1, s[0:1]
	v_lshl_add_u64 v[124:125], v[138:139], 1, s[0:1]
	s_waitcnt vmcnt(0)
	v_pk_mul_f32 v[194:195], v[14:15], v[202:203]
	v_pk_mul_f32 v[196:197], v[12:13], v[134:135]
	v_pk_add_f32 v[128:129], v[188:189], 1.0 op_sel_hi:[1,0]
	v_pk_add_f32 v[134:135], v[186:187], 1.0 op_sel_hi:[1,0]
	v_pk_mul_f32 v[198:199], v[10:11], v[198:199]
	v_pk_mul_f32 v[202:203], v[8:9], v[204:205]
	v_pk_add_f32 v[138:139], v[192:193], 1.0 op_sel_hi:[1,0]
	v_pk_add_f32 v[146:147], v[190:191], 1.0 op_sel_hi:[1,0]
	v_pk_fma_f32 v[188:189], v[128:129], v[194:195], v[6:7]
	v_pk_fma_f32 v[186:187], v[134:135], v[196:197], v[4:5]
	v_pk_fma_f32 v[190:191], v[138:139], v[198:199], v[2:3]
	v_pk_fma_f32 v[192:193], v[146:147], v[202:203], v[0:1]
	v_cvt_pk_bf16_f32 v186, v186, v187
	v_cvt_pk_bf16_f32 v187, v188, v189
	s_nop 0
	v_cvt_pk_bf16_f32 v188, v192, v193
	v_cvt_pk_bf16_f32 v189, v190, v191
	global_store_dwordx4 v[126:127], v[186:189], off
	ds_read_b32 v190, v184 offset:4160
	s_nop 0
	v_cvt_pk_bf16_f32 v186, v136, v137
	v_cvt_pk_bf16_f32 v187, v110, v111
	v_cvt_pk_bf16_f32 v188, v108, v109
	s_waitcnt lgkmcnt(0)
	v_pk_mul_f32 v[108:109], v[108:109], v[190:191] op_sel_hi:[1,0]
	v_cvt_pk_bf16_f32 v189, v106, v107
	v_pk_mul_f32 v[136:137], v[136:137], v[190:191] op_sel_hi:[1,0]
	v_pk_mul_f32 v[110:111], v[110:111], v[190:191] op_sel_hi:[1,0]
	v_pk_mul_f32 v[106:107], v[106:107], v[190:191] op_sel_hi:[1,0]
	v_pk_mul_f32 v[108:109], v[8:9], v[108:109]
	v_pk_mul_f32 v[110:111], v[14:15], v[110:111]
	v_pk_mul_f32 v[136:137], v[12:13], v[136:137]
	v_pk_mul_f32 v[106:107], v[10:11], v[106:107]
	v_pk_fma_f32 v[108:109], v[146:147], v[108:109], v[0:1]
	global_store_dwordx4 v[112:113], v[186:189], off
	v_pk_fma_f32 v[110:111], v[128:129], v[110:111], v[6:7]
	v_pk_fma_f32 v[136:137], v[134:135], v[136:137], v[4:5]
	v_pk_fma_f32 v[186:187], v[138:139], v[106:107], v[2:3]
	v_cvt_pk_bf16_f32 v106, v136, v137
	v_cvt_pk_bf16_f32 v107, v110, v111
	v_cvt_pk_bf16_f32 v108, v108, v109
	s_nop 0
	v_cvt_pk_bf16_f32 v109, v186, v187
	global_store_dwordx4 v[122:123], v[106:109], off
	ds_read_b32 v110, v184 offset:4224
	s_nop 0
	v_cvt_pk_bf16_f32 v106, v140, v141
	v_cvt_pk_bf16_f32 v107, v94, v95
	v_cvt_pk_bf16_f32 v108, v92, v93
	s_waitcnt lgkmcnt(0)
	v_pk_mul_f32 v[92:93], v[92:93], v[110:111] op_sel_hi:[1,0]
	v_cvt_pk_bf16_f32 v109, v90, v91
	global_store_dwordx4 v[96:97], v[106:109], off
	v_pk_mul_f32 v[94:95], v[94:95], v[110:111] op_sel_hi:[1,0]
	v_pk_mul_f32 v[90:91], v[90:91], v[110:111] op_sel_hi:[1,0]
	v_pk_mul_f32 v[106:107], v[140:141], v[110:111] op_sel_hi:[1,0]
	v_pk_mul_f32 v[92:93], v[8:9], v[92:93]
	v_pk_mul_f32 v[94:95], v[14:15], v[94:95]
	v_pk_mul_f32 v[106:107], v[12:13], v[106:107]
	v_pk_mul_f32 v[90:91], v[10:11], v[90:91]
	v_pk_fma_f32 v[92:93], v[146:147], v[92:93], v[0:1]
	v_pk_fma_f32 v[94:95], v[128:129], v[94:95], v[6:7]
	v_pk_fma_f32 v[106:107], v[134:135], v[106:107], v[4:5]
	v_pk_fma_f32 v[108:109], v[138:139], v[90:91], v[2:3]
	v_cvt_pk_bf16_f32 v90, v106, v107
	v_cvt_pk_bf16_f32 v91, v94, v95
	v_cvt_pk_bf16_f32 v92, v92, v93
	s_nop 0
	v_cvt_pk_bf16_f32 v93, v108, v109
	global_store_dwordx4 v[124:125], v[90:93], off
	ds_read_b32 v92, v184 offset:4288
	s_waitcnt lgkmcnt(0)
	v_pk_mul_f32 v[106:107], v[148:149], v[92:93] op_sel_hi:[1,0]
	v_lshlrev_b64 v[90:91], 10, v[142:143]
	v_lshl_add_u64 v[94:95], v[90:91], 0, v[132:133]
	v_cvt_pk_bf16_f32 v90, v148, v149
	v_cvt_pk_bf16_f32 v91, v78, v79
	v_pk_mul_f32 v[78:79], v[78:79], v[92:93] op_sel_hi:[1,0]
	v_pk_mul_f32 v[108:109], v[76:77], v[92:93] op_sel_hi:[1,0]
	v_pk_mul_f32 v[92:93], v[74:75], v[92:93] op_sel_hi:[1,0]
	v_pk_mul_f32 v[78:79], v[14:15], v[78:79]
	v_pk_mul_f32 v[106:107], v[12:13], v[106:107]
	v_pk_mul_f32 v[110:111], v[10:11], v[92:93]
	v_pk_mul_f32 v[108:109], v[8:9], v[108:109]
	v_cvt_pk_bf16_f32 v92, v76, v77
	v_cvt_pk_bf16_f32 v93, v74, v75
	v_pk_fma_f32 v[74:75], v[128:129], v[78:79], v[6:7]
	v_pk_fma_f32 v[76:77], v[134:135], v[106:107], v[4:5]
	global_store_dwordx4 v[80:81], v[90:93], off
	v_pk_fma_f32 v[78:79], v[146:147], v[108:109], v[0:1]
	v_cvt_pk_bf16_f32 v76, v76, v77
	v_cvt_pk_bf16_f32 v77, v74, v75
	v_lshl_add_u64 v[74:75], v[94:95], 1, s[0:1]
	v_pk_fma_f32 v[90:91], v[138:139], v[110:111], v[2:3]
	v_cvt_pk_bf16_f32 v78, v78, v79
	s_nop 0
	v_cvt_pk_bf16_f32 v79, v90, v91
	global_store_dwordx4 v[74:75], v[76:79], off
	ds_read_b32 v76, v184 offset:4608
	s_waitcnt lgkmcnt(0)
; __device__ __forceinline__ unsigned cvt_pk_bf16(float lo, float hi) { unsigned r; asm volatile("v_cvt_pk_bf16_f32 %0, %1, %2" : "=v"(r) : "v"(lo), "v"(hi)); return r; }
;     __device__ __forceinline__ void fused(f32x4 (&acc)[2][2][4][2], const Unit& u, int wr, int wc, int fr, int fq, LAS unsigned char* lds, int tid) const {
;     ...
;                 for (int m = 0; m < 4; ++m) { const int r = ai * HALF + wr * 64 + m * 16 + fr; const size_t off = (size_t)r * DM + c; const float rs = S[r];
;                     const f32x4 x0 = acc[ai][bj][m][0], x1 = acc[ai][bj][m][1]; const f32x4 y0 = x0 * rs * g0, y1 = x1 * rs * g1;
;                     if (MODE == 0) { { u32x4 wx; wx.x = cvt_pk_bf16(x0[0], x0[1]); wx.y = cvt_pk_bf16(x0[2], x0[3]); wx.z = cvt_pk_bf16(x1[0], x1[1]); wx.w = cvt_pk_bf16(x1[2], x1[3]); *(u32x4*)(xb_ + off) = wx; }
;                         const f32x4 z0 = y0 * sc0 + sh0, z1 = y1 * sc1 + sh1;
;                         u32x4 w; w.x = cvt_pk_bf16(z0[0], z0[1]); w.y = cvt_pk_bf16(z0[2], z0[3]); w.z = cvt_pk_bf16(z1[0], z1[1]); w.w = cvt_pk_bf16(z1[2], z1[3]);
;                         *(u32x4*)(XN + (size_t)u.pm * BM * DM + off) = w; }
;                     else { *(f32x4*)(out_ + off) = y0; *(f32x4*)(out_ + off + 4) = y1; } }
;             asm volatile("" ::: "memory"); }
	v_pk_mul_f32 v[92:93], v[62:63], v[76:77] op_sel_hi:[1,0]
	v_lshlrev_b64 v[78:79], 10, v[150:151]
	v_lshl_add_u64 v[90:91], v[78:79], 0, v[132:133]
	v_pk_mul_f32 v[78:79], v[152:153], v[76:77] op_sel_hi:[1,0]
	v_pk_mul_f32 v[92:93], v[14:15], v[92:93]
	v_pk_mul_f32 v[94:95], v[12:13], v[78:79]
	v_pk_mul_f32 v[78:79], v[60:61], v[76:77] op_sel_hi:[1,0]
	v_pk_mul_f32 v[76:77], v[58:59], v[76:77] op_sel_hi:[1,0]
	v_pk_mul_f32 v[108:109], v[8:9], v[78:79]
	v_pk_mul_f32 v[106:107], v[10:11], v[76:77]
	v_cvt_pk_bf16_f32 v76, v152, v153
	v_cvt_pk_bf16_f32 v77, v62, v63
	v_cvt_pk_bf16_f32 v78, v60, v61
	v_cvt_pk_bf16_f32 v79, v58, v59
	v_pk_fma_f32 v[58:59], v[128:129], v[92:93], v[6:7]
	v_pk_fma_f32 v[60:61], v[134:135], v[94:95], v[4:5]
	global_store_dwordx4 v[64:65], v[76:79], off
	v_pk_fma_f32 v[62:63], v[146:147], v[108:109], v[0:1]
	v_cvt_pk_bf16_f32 v60, v60, v61
	v_cvt_pk_bf16_f32 v61, v58, v59
	v_lshl_add_u64 v[58:59], v[90:91], 1, s[0:1]
	v_pk_fma_f32 v[76:77], v[138:139], v[106:107], v[2:3]
	v_cvt_pk_bf16_f32 v62, v62, v63
	s_nop 0
	v_cvt_pk_bf16_f32 v63, v76, v77
	global_store_dwordx4 v[58:59], v[60:63], off
	ds_read_b32 v60, v184 offset:4672
	s_waitcnt lgkmcnt(0)
	v_pk_mul_f32 v[78:79], v[46:47], v[60:61] op_sel_hi:[1,0]
	v_lshlrev_b64 v[62:63], 10, v[154:155]
	v_lshl_add_u64 v[76:77], v[62:63], 0, v[132:133]
	v_pk_mul_f32 v[62:63], v[158:159], v[60:61] op_sel_hi:[1,0]
	v_pk_mul_f32 v[78:79], v[14:15], v[78:79]
	v_pk_mul_f32 v[90:91], v[12:13], v[62:63]
	v_pk_mul_f32 v[62:63], v[156:157], v[60:61] op_sel_hi:[1,0]
	v_pk_mul_f32 v[60:61], v[44:45], v[60:61] op_sel_hi:[1,0]
	v_pk_mul_f32 v[94:95], v[8:9], v[62:63]
	v_pk_mul_f32 v[92:93], v[10:11], v[60:61]
	v_cvt_pk_bf16_f32 v60, v158, v159
	v_cvt_pk_bf16_f32 v61, v46, v47
	v_cvt_pk_bf16_f32 v62, v156, v157
	v_cvt_pk_bf16_f32 v63, v44, v45
	v_pk_fma_f32 v[44:45], v[128:129], v[78:79], v[6:7]
	global_store_dwordx4 v[48:49], v[60:63], off
	v_pk_fma_f32 v[46:47], v[134:135], v[90:91], v[4:5]
	v_pk_fma_f32 v[78:79], v[138:139], v[92:93], v[2:3]
	v_pk_fma_f32 v[62:63], v[146:147], v[94:95], v[0:1]
	v_cvt_pk_bf16_f32 v60, v46, v47
	v_cvt_pk_bf16_f32 v61, v44, v45
	v_lshl_add_u64 v[44:45], v[76:77], 1, s[0:1]
	v_cvt_pk_bf16_f32 v62, v62, v63
	v_cvt_pk_bf16_f32 v63, v78, v79
	global_store_dwordx4 v[44:45], v[60:63], off
	ds_read_b32 v46, v184 offset:4736
	s_nop 0
	v_lshlrev_b64 v[60:61], 10, v[160:161]
	v_lshl_add_u64 v[76:77], v[60:61], 0, v[132:133]
	s_waitcnt lgkmcnt(0)
	v_pk_mul_f32 v[60:61], v[168:169], v[46:47] op_sel_hi:[1,0]
	v_pk_mul_f32 v[62:63], v[164:165], v[46:47] op_sel_hi:[1,0]
	v_pk_mul_f32 v[90:91], v[12:13], v[60:61]
	v_pk_mul_f32 v[60:61], v[166:167], v[46:47] op_sel_hi:[1,0]
	v_pk_mul_f32 v[46:47], v[162:163], v[46:47] op_sel_hi:[1,0]
	v_pk_mul_f32 v[78:79], v[14:15], v[62:63]
	v_pk_mul_f32 v[46:47], v[10:11], v[46:47]
	v_pk_mul_f32 v[92:93], v[8:9], v[60:61]
	v_cvt_pk_bf16_f32 v60, v168, v169
	v_cvt_pk_bf16_f32 v61, v164, v165
	v_cvt_pk_bf16_f32 v62, v166, v167
	v_cvt_pk_bf16_f32 v63, v162, v163
	global_store_dwordx4 v[32:33], v[60:63], off
	v_pk_fma_f32 v[46:47], v[138:139], v[46:47], v[2:3]
	s_nop 0
	v_pk_fma_f32 v[62:63], v[128:129], v[78:79], v[6:7]
	v_pk_fma_f32 v[60:61], v[134:135], v[90:91], v[4:5]
	v_pk_fma_f32 v[78:79], v[146:147], v[92:93], v[0:1]
	v_cvt_pk_bf16_f32 v60, v60, v61
	v_cvt_pk_bf16_f32 v61, v62, v63
	s_nop 0
	v_cvt_pk_bf16_f32 v62, v78, v79
	v_cvt_pk_bf16_f32 v63, v46, v47
	v_lshl_add_u64 v[46:47], v[76:77], 1, s[0:1]
	global_store_dwordx4 v[46:47], v[60:63], off
	ds_read_b32 v60, v184 offset:4800
	s_waitcnt lgkmcnt(0)
	v_pk_mul_f32 v[76:77], v[178:179], v[60:61] op_sel_hi:[1,0]
	v_lshlrev_b64 v[62:63], 10, v[170:171]
	v_pk_mul_f32 v[78:79], v[174:175], v[60:61] op_sel_hi:[1,0]
	v_pk_mul_f32 v[12:13], v[12:13], v[76:77]
	v_pk_mul_f32 v[76:77], v[176:177], v[60:61] op_sel_hi:[1,0]
	v_pk_mul_f32 v[60:61], v[172:173], v[60:61] op_sel_hi:[1,0]
	v_lshl_add_u64 v[62:63], v[62:63], 0, v[132:133]
	v_pk_mul_f32 v[60:61], v[10:11], v[60:61]
	v_pk_mul_f32 v[76:77], v[8:9], v[76:77]
	v_cvt_pk_bf16_f32 v8, v178, v179
	v_cvt_pk_bf16_f32 v9, v174, v175
	v_pk_mul_f32 v[14:15], v[14:15], v[78:79]
	v_cvt_pk_bf16_f32 v10, v176, v177
	v_cvt_pk_bf16_f32 v11, v172, v173
	global_store_dwordx4 v[16:17], v[8:11], off
	v_pk_fma_f32 v[6:7], v[128:129], v[14:15], v[6:7]
	v_pk_fma_f32 v[4:5], v[134:135], v[12:13], v[4:5]
	v_pk_fma_f32 v[8:9], v[138:139], v[60:61], v[2:3]
	v_pk_fma_f32 v[2:3], v[146:147], v[76:77], v[0:1]
	v_lshl_add_u64 v[60:61], v[62:63], 1, s[0:1]
	v_cvt_pk_bf16_f32 v0, v4, v5
	v_cvt_pk_bf16_f32 v1, v6, v7
	v_cvt_pk_bf16_f32 v2, v2, v3
	v_cvt_pk_bf16_f32 v3, v8, v9
	global_store_dwordx4 v[60:61], v[0:3], off
	global_load_dwordx4 v[76:79], v[180:181], off offset:512
	global_load_dwordx4 v[90:93], v[180:181], off offset:528
	global_load_dwordx4 v[12:15], v[144:145], off offset:512
	global_load_dwordx4 v[8:11], v[144:145], off offset:528
	global_load_dwordx4 v[4:7], v[182:183], off offset:512
	global_load_dwordx4 v[0:3], v[182:183], off offset:528
	ds_read_b32 v94, v184 offset:4096
	s_waitcnt lgkmcnt(0)
	v_pk_mul_f32 v[106:107], v[118:119], v[94:95] op_sel_hi:[1,0]
	s_waitcnt vmcnt(0)
; __device__ __forceinline__ unsigned cvt_pk_bf16(float lo, float hi) { unsigned r; asm volatile("v_cvt_pk_bf16_f32 %0, %1, %2" : "=v"(r) : "v"(lo), "v"(hi)); return r; }
;     __device__ __forceinline__ void fused(f32x4 (&acc)[2][2][4][2], const Unit& u, int wr, int wc, int fr, int fq, LAS unsigned char* lds, int tid) const {
;     ...
;                 for (int m = 0; m < 4; ++m) { const int r = ai * HALF + wr * 64 + m * 16 + fr; const size_t off = (size_t)r * DM + c; const float rs = S[r];
;                     const f32x4 x0 = acc[ai][bj][m][0], x1 = acc[ai][bj][m][1]; const f32x4 y0 = x0 * rs * g0, y1 = x1 * rs * g1;
;                     if (MODE == 0) { { u32x4 wx; wx.x = cvt_pk_bf16(x0[0], x0[1]); wx.y = cvt_pk_bf16(x0[2], x0[3]); wx.z = cvt_pk_bf16(x1[0], x1[1]); wx.w = cvt_pk_bf16(x1[2], x1[3]); *(u32x4*)(xb_ + off) = wx; }
;                         const f32x4 z0 = y0 * sc0 + sh0, z1 = y1 * sc1 + sh1;
;                         u32x4 w; w.x = cvt_pk_bf16(z0[0], z0[1]); w.y = cvt_pk_bf16(z0[2], z0[3]); w.z = cvt_pk_bf16(z1[0], z1[1]); w.w = cvt_pk_bf16(z1[2], z1[3]);
;                         *(u32x4*)(XN + (size_t)u.pm * BM * DM + off) = w; }
;                     else { *(f32x4*)(out_ + off) = y0; *(f32x4*)(out_ + off + 4) = y1; } }
;             asm volatile("" ::: "memory"); }
	v_pk_add_f32 v[62:63], v[78:79], 1.0 op_sel_hi:[1,0]
	v_pk_add_f32 v[78:79], v[92:93], 1.0 op_sel_hi:[1,0]
	v_pk_mul_f32 v[92:93], v[116:117], v[94:95] op_sel_hi:[1,0]
	v_pk_add_f32 v[76:77], v[76:77], 1.0 op_sel_hi:[1,0]
	v_pk_mul_f32 v[108:109], v[12:13], v[92:93]
	v_pk_mul_f32 v[92:93], v[120:121], v[94:95] op_sel_hi:[1,0]
	v_pk_mul_f32 v[94:95], v[114:115], v[94:95] op_sel_hi:[1,0]
	v_pk_mul_f32 v[106:107], v[14:15], v[106:107]
	v_pk_mul_f32 v[110:111], v[10:11], v[94:95]
	v_pk_mul_f32 v[128:129], v[8:9], v[92:93]
	v_cvt_pk_bf16_f32 v92, v116, v117
	v_cvt_pk_bf16_f32 v93, v118, v119
	v_cvt_pk_bf16_f32 v94, v120, v121
	v_cvt_pk_bf16_f32 v95, v114, v115
	v_pk_add_f32 v[90:91], v[90:91], 1.0 op_sel_hi:[1,0]
	global_store_dwordx4 v[130:131], v[92:95], off offset:256
	s_nop 1
	v_pk_fma_f32 v[94:95], v[62:63], v[106:107], v[6:7]
	v_pk_fma_f32 v[92:93], v[76:77], v[108:109], v[4:5]
	v_pk_fma_f32 v[106:107], v[78:79], v[110:111], v[2:3]
	v_pk_fma_f32 v[108:109], v[90:91], v[128:129], v[0:1]
	v_cvt_pk_bf16_f32 v92, v92, v93
	v_cvt_pk_bf16_f32 v93, v94, v95
	s_nop 0
	v_cvt_pk_bf16_f32 v94, v108, v109
	v_cvt_pk_bf16_f32 v95, v106, v107
	global_store_dwordx4 v[126:127], v[92:95], off offset:256
	ds_read_b32 v92, v184 offset:4160
	s_waitcnt lgkmcnt(0)
	v_pk_mul_f32 v[106:107], v[102:103], v[92:93] op_sel_hi:[1,0]
	v_pk_mul_f32 v[94:95], v[100:101], v[92:93] op_sel_hi:[1,0]
	v_pk_mul_f32 v[106:107], v[14:15], v[106:107]
	v_pk_mul_f32 v[108:109], v[12:13], v[94:95]
	v_pk_mul_f32 v[94:95], v[104:105], v[92:93] op_sel_hi:[1,0]
	v_pk_mul_f32 v[92:93], v[98:99], v[92:93] op_sel_hi:[1,0]
	v_pk_mul_f32 v[114:115], v[8:9], v[94:95]
	v_pk_mul_f32 v[110:111], v[10:11], v[92:93]
	v_cvt_pk_bf16_f32 v92, v100, v101
	v_cvt_pk_bf16_f32 v93, v102, v103
	v_cvt_pk_bf16_f32 v94, v104, v105
	v_cvt_pk_bf16_f32 v95, v98, v99
	global_store_dwordx4 v[112:113], v[92:95], off offset:256
	v_pk_fma_f32 v[98:99], v[78:79], v[110:111], v[2:3]
	v_pk_fma_f32 v[100:101], v[90:91], v[114:115], v[0:1]
	v_pk_fma_f32 v[94:95], v[62:63], v[106:107], v[6:7]
	v_pk_fma_f32 v[92:93], v[76:77], v[108:109], v[4:5]
	s_nop 0
	v_cvt_pk_bf16_f32 v92, v92, v93
	v_cvt_pk_bf16_f32 v93, v94, v95
	v_cvt_pk_bf16_f32 v94, v100, v101
	v_cvt_pk_bf16_f32 v95, v98, v99
	global_store_dwordx4 v[122:123], v[92:95], off offset:256
	ds_read_b32 v92, v184 offset:4224
	s_waitcnt lgkmcnt(0)
	v_pk_mul_f32 v[98:99], v[86:87], v[92:93] op_sel_hi:[1,0]
	v_pk_mul_f32 v[94:95], v[84:85], v[92:93] op_sel_hi:[1,0]
	v_pk_mul_f32 v[98:99], v[14:15], v[98:99]
	v_pk_mul_f32 v[94:95], v[12:13], v[94:95]
	v_pk_mul_f32 v[100:101], v[88:89], v[92:93] op_sel_hi:[1,0]
	v_pk_mul_f32 v[92:93], v[82:83], v[92:93] op_sel_hi:[1,0]
	v_cvt_pk_bf16_f32 v84, v84, v85
	v_cvt_pk_bf16_f32 v85, v86, v87
	v_pk_mul_f32 v[100:101], v[8:9], v[100:101]
	v_pk_mul_f32 v[92:93], v[10:11], v[92:93]
	v_cvt_pk_bf16_f32 v86, v88, v89
	v_cvt_pk_bf16_f32 v87, v82, v83
	global_store_dwordx4 v[96:97], v[84:87], off offset:256
	v_pk_fma_f32 v[82:83], v[76:77], v[94:95], v[4:5]
	v_pk_fma_f32 v[88:89], v[90:91], v[100:101], v[0:1]
	v_pk_fma_f32 v[84:85], v[62:63], v[98:99], v[6:7]
	v_pk_fma_f32 v[86:87], v[78:79], v[92:93], v[2:3]
	v_cvt_pk_bf16_f32 v82, v82, v83
	v_cvt_pk_bf16_f32 v83, v84, v85
	v_cvt_pk_bf16_f32 v84, v88, v89
	s_nop 0
	v_cvt_pk_bf16_f32 v85, v86, v87
	global_store_dwordx4 v[124:125], v[82:85], off offset:256
	ds_read_b32 v82, v184 offset:4288
	s_waitcnt lgkmcnt(0)
	v_pk_mul_f32 v[86:87], v[70:71], v[82:83] op_sel_hi:[1,0]
	v_pk_mul_f32 v[84:85], v[68:69], v[82:83] op_sel_hi:[1,0]
	v_pk_mul_f32 v[86:87], v[14:15], v[86:87]
	v_pk_mul_f32 v[84:85], v[12:13], v[84:85]
	v_pk_mul_f32 v[88:89], v[72:73], v[82:83] op_sel_hi:[1,0]
	v_pk_mul_f32 v[82:83], v[66:67], v[82:83] op_sel_hi:[1,0]
	v_cvt_pk_bf16_f32 v68, v68, v69
	v_cvt_pk_bf16_f32 v69, v70, v71
	v_pk_mul_f32 v[88:89], v[8:9], v[88:89]
	v_pk_mul_f32 v[82:83], v[10:11], v[82:83]
	v_cvt_pk_bf16_f32 v70, v72, v73
	v_cvt_pk_bf16_f32 v71, v66, v67
	global_store_dwordx4 v[80:81], v[68:71], off offset:256
	v_pk_fma_f32 v[66:67], v[76:77], v[84:85], v[4:5]
	v_pk_fma_f32 v[72:73], v[90:91], v[88:89], v[0:1]
	v_pk_fma_f32 v[68:69], v[62:63], v[86:87], v[6:7]
	v_pk_fma_f32 v[70:71], v[78:79], v[82:83], v[2:3]
	v_cvt_pk_bf16_f32 v66, v66, v67
	v_cvt_pk_bf16_f32 v67, v68, v69
	v_cvt_pk_bf16_f32 v68, v72, v73
	s_nop 0
	v_cvt_pk_bf16_f32 v69, v70, v71
	global_store_dwordx4 v[74:75], v[66:69], off offset:256
	ds_read_b32 v66, v184 offset:4608
	s_waitcnt lgkmcnt(0)
; __device__ __forceinline__ unsigned cvt_pk_bf16(float lo, float hi) { unsigned r; asm volatile("v_cvt_pk_bf16_f32 %0, %1, %2" : "=v"(r) : "v"(lo), "v"(hi)); return r; }
;     __device__ __forceinline__ void fused(f32x4 (&acc)[2][2][4][2], const Unit& u, int wr, int wc, int fr, int fq, LAS unsigned char* lds, int tid) const {
;     ...
;                 for (int m = 0; m < 4; ++m) { const int r = ai * HALF + wr * 64 + m * 16 + fr; const size_t off = (size_t)r * DM + c; const float rs = S[r];
;                     const f32x4 x0 = acc[ai][bj][m][0], x1 = acc[ai][bj][m][1]; const f32x4 y0 = x0 * rs * g0, y1 = x1 * rs * g1;
;                     if (MODE == 0) { { u32x4 wx; wx.x = cvt_pk_bf16(x0[0], x0[1]); wx.y = cvt_pk_bf16(x0[2], x0[3]); wx.z = cvt_pk_bf16(x1[0], x1[1]); wx.w = cvt_pk_bf16(x1[2], x1[3]); *(u32x4*)(xb_ + off) = wx; }
;                         const f32x4 z0 = y0 * sc0 + sh0, z1 = y1 * sc1 + sh1;
;                         u32x4 w; w.x = cvt_pk_bf16(z0[0], z0[1]); w.y = cvt_pk_bf16(z0[2], z0[3]); w.z = cvt_pk_bf16(z1[0], z1[1]); w.w = cvt_pk_bf16(z1[2], z1[3]);
;                         *(u32x4*)(XN + (size_t)u.pm * BM * DM + off) = w; }
;                     else { *(f32x4*)(out_ + off) = y0; *(f32x4*)(out_ + off + 4) = y1; } }
;             asm volatile("" ::: "memory"); }
;         asm volatile("s_waitcnt lgkmcnt(0)" ::: "memory"); __builtin_amdgcn_s_barrier(); asm volatile("" ::: "memory");
	v_pk_mul_f32 v[70:71], v[54:55], v[66:67] op_sel_hi:[1,0]
	v_pk_mul_f32 v[68:69], v[52:53], v[66:67] op_sel_hi:[1,0]
	v_pk_mul_f32 v[70:71], v[14:15], v[70:71]
	v_pk_mul_f32 v[68:69], v[12:13], v[68:69]
	v_pk_mul_f32 v[72:73], v[56:57], v[66:67] op_sel_hi:[1,0]
	v_pk_mul_f32 v[66:67], v[50:51], v[66:67] op_sel_hi:[1,0]
	v_cvt_pk_bf16_f32 v52, v52, v53
	v_cvt_pk_bf16_f32 v53, v54, v55
	v_pk_mul_f32 v[72:73], v[8:9], v[72:73]
	v_pk_mul_f32 v[66:67], v[10:11], v[66:67]
	v_cvt_pk_bf16_f32 v54, v56, v57
	v_cvt_pk_bf16_f32 v55, v50, v51
	global_store_dwordx4 v[64:65], v[52:55], off offset:256
	v_pk_fma_f32 v[50:51], v[76:77], v[68:69], v[4:5]
	v_pk_fma_f32 v[56:57], v[90:91], v[72:73], v[0:1]
	v_pk_fma_f32 v[52:53], v[62:63], v[70:71], v[6:7]
	v_pk_fma_f32 v[54:55], v[78:79], v[66:67], v[2:3]
	v_cvt_pk_bf16_f32 v50, v50, v51
	v_cvt_pk_bf16_f32 v51, v52, v53
	v_cvt_pk_bf16_f32 v52, v56, v57
	s_nop 0
	v_cvt_pk_bf16_f32 v53, v54, v55
	global_store_dwordx4 v[58:59], v[50:53], off offset:256
	ds_read_b32 v50, v184 offset:4672
	s_waitcnt lgkmcnt(0)
	v_pk_mul_f32 v[54:55], v[38:39], v[50:51] op_sel_hi:[1,0]
	v_pk_mul_f32 v[52:53], v[36:37], v[50:51] op_sel_hi:[1,0]
	v_pk_mul_f32 v[54:55], v[14:15], v[54:55]
	v_pk_mul_f32 v[52:53], v[12:13], v[52:53]
	v_pk_mul_f32 v[56:57], v[40:41], v[50:51] op_sel_hi:[1,0]
	v_pk_mul_f32 v[50:51], v[34:35], v[50:51] op_sel_hi:[1,0]
	v_cvt_pk_bf16_f32 v36, v36, v37
	v_cvt_pk_bf16_f32 v37, v38, v39
	v_pk_mul_f32 v[56:57], v[8:9], v[56:57]
	v_pk_mul_f32 v[50:51], v[10:11], v[50:51]
	v_cvt_pk_bf16_f32 v38, v40, v41
	v_cvt_pk_bf16_f32 v39, v34, v35
	global_store_dwordx4 v[48:49], v[36:39], off offset:256
	v_pk_fma_f32 v[34:35], v[76:77], v[52:53], v[4:5]
	v_pk_fma_f32 v[40:41], v[90:91], v[56:57], v[0:1]
	v_pk_fma_f32 v[36:37], v[62:63], v[54:55], v[6:7]
	v_pk_fma_f32 v[38:39], v[78:79], v[50:51], v[2:3]
	v_cvt_pk_bf16_f32 v34, v34, v35
	v_cvt_pk_bf16_f32 v35, v36, v37
	v_cvt_pk_bf16_f32 v36, v40, v41
	s_nop 0
	v_cvt_pk_bf16_f32 v37, v38, v39
	global_store_dwordx4 v[44:45], v[34:37], off offset:256
	ds_read_b32 v34, v184 offset:4736
	s_waitcnt lgkmcnt(0)
	v_pk_mul_f32 v[38:39], v[22:23], v[34:35] op_sel_hi:[1,0]
	v_pk_mul_f32 v[36:37], v[20:21], v[34:35] op_sel_hi:[1,0]
	v_pk_mul_f32 v[38:39], v[14:15], v[38:39]
	v_pk_mul_f32 v[36:37], v[12:13], v[36:37]
	v_pk_mul_f32 v[40:41], v[24:25], v[34:35] op_sel_hi:[1,0]
	v_pk_mul_f32 v[34:35], v[18:19], v[34:35] op_sel_hi:[1,0]
	v_cvt_pk_bf16_f32 v20, v20, v21
	v_cvt_pk_bf16_f32 v21, v22, v23
	v_pk_mul_f32 v[40:41], v[8:9], v[40:41]
	v_pk_mul_f32 v[34:35], v[10:11], v[34:35]
	v_cvt_pk_bf16_f32 v22, v24, v25
	v_cvt_pk_bf16_f32 v23, v18, v19
	global_store_dwordx4 v[32:33], v[20:23], off offset:256
	v_pk_fma_f32 v[18:19], v[76:77], v[36:37], v[4:5]
	v_pk_fma_f32 v[24:25], v[90:91], v[40:41], v[0:1]
	v_pk_fma_f32 v[20:21], v[62:63], v[38:39], v[6:7]
	v_pk_fma_f32 v[22:23], v[78:79], v[34:35], v[2:3]
	v_cvt_pk_bf16_f32 v18, v18, v19
	v_cvt_pk_bf16_f32 v19, v20, v21
	v_cvt_pk_bf16_f32 v20, v24, v25
	s_nop 0
	v_cvt_pk_bf16_f32 v21, v22, v23
	global_store_dwordx4 v[46:47], v[18:21], off offset:256
	ds_read_b32 v18, v184 offset:4800
	s_waitcnt lgkmcnt(0)
	v_pk_mul_f32 v[22:23], v[26:27], v[18:19] op_sel_hi:[1,0]
	v_pk_mul_f32 v[20:21], v[30:31], v[18:19] op_sel_hi:[1,0]
	v_pk_mul_f32 v[14:15], v[14:15], v[22:23]
	v_pk_mul_f32 v[12:13], v[12:13], v[20:21]
	v_pk_mul_f32 v[20:21], v[42:43], v[18:19] op_sel_hi:[1,0]
	v_pk_mul_f32 v[18:19], v[28:29], v[18:19] op_sel_hi:[1,0]
	v_pk_mul_f32 v[20:21], v[8:9], v[20:21]
	v_pk_mul_f32 v[18:19], v[10:11], v[18:19]
	v_cvt_pk_bf16_f32 v8, v30, v31
	v_cvt_pk_bf16_f32 v9, v26, v27
	v_cvt_pk_bf16_f32 v10, v42, v43
	v_cvt_pk_bf16_f32 v11, v28, v29
	global_store_dwordx4 v[16:17], v[8:11], off offset:256
	v_pk_fma_f32 v[6:7], v[62:63], v[14:15], v[6:7]
	v_pk_fma_f32 v[4:5], v[76:77], v[12:13], v[4:5]
	v_pk_fma_f32 v[8:9], v[78:79], v[18:19], v[2:3]
	v_pk_fma_f32 v[2:3], v[90:91], v[20:21], v[0:1]
	v_cvt_pk_bf16_f32 v0, v4, v5
	v_cvt_pk_bf16_f32 v1, v6, v7
	s_nop 0
	v_cvt_pk_bf16_f32 v2, v2, v3
	v_cvt_pk_bf16_f32 v3, v8, v9
	global_store_dwordx4 v[60:61], v[0:3], off offset:256
	s_waitcnt lgkmcnt(0)
	s_barrier

; __device__ __forceinline__ unsigned cvt_pk_bf16(float lo, float hi) { unsigned r; asm volatile("v_cvt_pk_bf16_f32 %0, %1, %2" : "=v"(r) : "v"(lo), "v"(hi)); return r; }
;     __device__ __forceinline__ void fused(f32x4 (&acc)[2][2][4][2], const Unit& u, int wr, int wc, int fr, int fq, LAS unsigned char* lds, int tid) const {
;     ...
;         for (int bj = 0; bj < 2; ++bj) { const int c = col0 + bj * HALF;
;             const f32x4 g0 = *(const f32x4*)(g + c), g1 = *(const f32x4*)(g + c + 4);
;             f32x4 sc0 = {0.f, 0.f, 0.f, 0.f}, sc1 = sc0, sh0 = sc0, sh1 = sc0;
;             if (MODE == 0) { sc0 = *(const f32x4*)(scale + (size_t)cls * MODLD + c) + 1.0f; sc1 = *(const f32x4*)(scale + (size_t)cls * MODLD + c + 4) + 1.0f;
;                 sh0 = *(const f32x4*)(shift + (size_t)cls * MODLD + c); sh1 = *(const f32x4*)(shift + (size_t)cls * MODLD + c + 4); }
; #pragma unroll
;             for (int ai = 0; ai < 2; ++ai)
; #pragma unroll
;                 for (int m = 0; m < 4; ++m) { const int r = ai * HALF + wr * 64 + m * 16 + fr; const size_t off = (size_t)r * DM + c; const float rs = S[r];
;                     const f32x4 x0 = acc[ai][bj][m][0], x1 = acc[ai][bj][m][1]; const f32x4 y0 = x0 * rs * g0, y1 = x1 * rs * g1;
;                     if (MODE == 0) { { u32x4 wx; wx.x = cvt_pk_bf16(x0[0], x0[1]); wx.y = cvt_pk_bf16(x0[2], x0[3]); wx.z = cvt_pk_bf16(x1[0], x1[1]); wx.w = cvt_pk_bf16(x1[2], x1[3]); *(u32x4*)(xb_ + off) = wx; }
;                         const f32x4 z0 = y0 * sc0 + sh0, z1 = y1 * sc1 + sh1;
;                         u32x4 w; w.x = cvt_pk_bf16(z0[0], z0[1]); w.y = cvt_pk_bf16(z0[2], z0[3]); w.z = cvt_pk_bf16(z1[0], z1[1]); w.w = cvt_pk_bf16(z1[2], z1[3]);
;                         *(u32x4*)(XN + (size_t)u.pm * BM * DM + off) = w; }
;                     else { *(f32x4*)(out_ + off) = y0; *(f32x4*)(out_ + off + 4) = y1; } }
.LBB0_1443:
	s_or_b64 exec, exec, s[18:19]
	v_lshlrev_b64 v[128:129], 2, v[132:133]
	s_waitcnt lgkmcnt(0)
	s_barrier
	v_lshl_add_u64 v[132:133], s[8:9], 0, v[128:129]
	global_load_dwordx4 v[4:7], v[132:133], off
	s_waitcnt lgkmcnt(0)
	global_load_dwordx4 v[0:3], v[132:133], off offset:16
	v_lshl_add_u32 v150, v130, 2, 0
	ds_read_b32 v144, v150 offset:4096
	s_lshl_b64 s[0:1], s[16:17], 2
	s_add_u32 s0, s2, s0
	s_addc_u32 s1, s3, s1
	v_lshlrev_b64 v[130:131], 12, v[130:131]
	v_lshl_add_u64 v[146:147], s[0:1], 0, v[128:129]
	s_waitcnt lgkmcnt(0)
	v_pk_mul_f32 v[124:125], v[124:125], v[144:145] op_sel_hi:[1,0]
	v_pk_mul_f32 v[126:127], v[126:127], v[144:145] op_sel_hi:[1,0]
	v_lshl_add_u64 v[128:129], v[146:147], 0, v[130:131]
	v_pk_mul_f32 v[130:131], v[120:121], v[144:145] op_sel_hi:[1,0]
	v_pk_mul_f32 v[144:145], v[122:123], v[144:145] op_sel_hi:[1,0]
	s_waitcnt vmcnt(0)
	v_pk_mul_f32 v[122:123], v[6:7], v[126:127]
	v_pk_mul_f32 v[120:121], v[4:5], v[124:125]
	v_pk_mul_f32 v[126:127], v[2:3], v[144:145]
	v_pk_mul_f32 v[124:125], v[0:1], v[130:131]
	global_store_dwordx4 v[128:129], v[120:123], off
	global_store_dwordx4 v[128:129], v[124:127], off offset:16
	ds_read_b32 v122, v150 offset:4160
	v_lshlrev_b64 v[120:121], 12, v[134:135]
	v_lshl_add_u64 v[120:121], v[146:147], 0, v[120:121]
	s_waitcnt lgkmcnt(0)
	v_pk_mul_f32 v[108:109], v[108:109], v[122:123] op_sel_hi:[1,0]
	v_pk_mul_f32 v[110:111], v[110:111], v[122:123] op_sel_hi:[1,0]
	v_pk_mul_f32 v[124:125], v[104:105], v[122:123] op_sel_hi:[1,0]
	v_pk_mul_f32 v[122:123], v[106:107], v[122:123] op_sel_hi:[1,0]
	v_pk_mul_f32 v[106:107], v[6:7], v[110:111]
	v_pk_mul_f32 v[104:105], v[4:5], v[108:109]
	v_pk_mul_f32 v[110:111], v[2:3], v[122:123]
	v_pk_mul_f32 v[108:109], v[0:1], v[124:125]
	global_store_dwordx4 v[120:121], v[104:107], off
	global_store_dwordx4 v[120:121], v[108:111], off offset:16
	ds_read_b32 v106, v150 offset:4224
	v_lshlrev_b64 v[104:105], 12, v[136:137]
	v_lshl_add_u64 v[104:105], v[146:147], 0, v[104:105]
	s_waitcnt lgkmcnt(0)
	v_pk_mul_f32 v[92:93], v[92:93], v[106:107] op_sel_hi:[1,0]
	v_pk_mul_f32 v[94:95], v[94:95], v[106:107] op_sel_hi:[1,0]
	v_pk_mul_f32 v[108:109], v[88:89], v[106:107] op_sel_hi:[1,0]
	v_pk_mul_f32 v[106:107], v[90:91], v[106:107] op_sel_hi:[1,0]
	v_pk_mul_f32 v[90:91], v[6:7], v[94:95]
	v_pk_mul_f32 v[88:89], v[4:5], v[92:93]
	v_pk_mul_f32 v[94:95], v[2:3], v[106:107]
	v_pk_mul_f32 v[92:93], v[0:1], v[108:109]
	global_store_dwordx4 v[104:105], v[88:91], off
	global_store_dwordx4 v[104:105], v[92:95], off offset:16
	ds_read_b32 v90, v150 offset:4288
	v_lshlrev_b64 v[88:89], 12, v[138:139]
	v_lshl_add_u64 v[88:89], v[146:147], 0, v[88:89]
	s_waitcnt lgkmcnt(0)
	v_pk_mul_f32 v[76:77], v[76:77], v[90:91] op_sel_hi:[1,0]
	v_pk_mul_f32 v[78:79], v[78:79], v[90:91] op_sel_hi:[1,0]
	v_pk_mul_f32 v[92:93], v[72:73], v[90:91] op_sel_hi:[1,0]
	v_pk_mul_f32 v[90:91], v[74:75], v[90:91] op_sel_hi:[1,0]
	v_pk_mul_f32 v[74:75], v[6:7], v[78:79]
	v_pk_mul_f32 v[72:73], v[4:5], v[76:77]
	v_pk_mul_f32 v[78:79], v[2:3], v[90:91]
	v_pk_mul_f32 v[76:77], v[0:1], v[92:93]
	global_store_dwordx4 v[88:89], v[72:75], off
	global_store_dwordx4 v[88:89], v[76:79], off offset:16
	ds_read_b32 v74, v150 offset:4608
	v_lshlrev_b64 v[72:73], 12, v[140:141]
	v_lshl_add_u64 v[72:73], v[146:147], 0, v[72:73]
	s_waitcnt lgkmcnt(0)
	v_pk_mul_f32 v[60:61], v[60:61], v[74:75] op_sel_hi:[1,0]
	v_pk_mul_f32 v[62:63], v[62:63], v[74:75] op_sel_hi:[1,0]
	v_pk_mul_f32 v[76:77], v[56:57], v[74:75] op_sel_hi:[1,0]
	v_pk_mul_f32 v[74:75], v[58:59], v[74:75] op_sel_hi:[1,0]
	v_pk_mul_f32 v[58:59], v[6:7], v[62:63]
	v_pk_mul_f32 v[56:57], v[4:5], v[60:61]
	v_pk_mul_f32 v[62:63], v[2:3], v[74:75]
	v_pk_mul_f32 v[60:61], v[0:1], v[76:77]
	global_store_dwordx4 v[72:73], v[56:59], off
	global_store_dwordx4 v[72:73], v[60:63], off offset:16
	ds_read_b32 v56, v150 offset:4672
	v_lshlrev_b64 v[58:59], 12, v[142:143]
	v_lshl_add_u64 v[58:59], v[146:147], 0, v[58:59]
	s_waitcnt lgkmcnt(0)
	v_pk_mul_f32 v[44:45], v[44:45], v[56:57] op_sel_hi:[1,0]
	v_pk_mul_f32 v[46:47], v[46:47], v[56:57] op_sel_hi:[1,0]
	v_pk_mul_f32 v[60:61], v[40:41], v[56:57] op_sel_hi:[1,0]
	v_pk_mul_f32 v[56:57], v[42:43], v[56:57] op_sel_hi:[1,0]
	v_pk_mul_f32 v[42:43], v[6:7], v[46:47]
	v_pk_mul_f32 v[40:41], v[4:5], v[44:45]
	v_pk_mul_f32 v[46:47], v[2:3], v[56:57]
	v_pk_mul_f32 v[44:45], v[0:1], v[60:61]
	global_store_dwordx4 v[58:59], v[40:43], off
	global_store_dwordx4 v[58:59], v[44:47], off offset:16
	ds_read_b32 v40, v150 offset:4736
	v_lshlrev_b64 v[42:43], 12, v[162:163]
	v_lshl_add_u64 v[42:43], v[146:147], 0, v[42:43]
	s_waitcnt lgkmcnt(0)
	v_pk_mul_f32 v[28:29], v[28:29], v[40:41] op_sel_hi:[1,0]
	v_pk_mul_f32 v[30:31], v[30:31], v[40:41] op_sel_hi:[1,0]
	v_pk_mul_f32 v[44:45], v[24:25], v[40:41] op_sel_hi:[1,0]
	v_pk_mul_f32 v[40:41], v[26:27], v[40:41] op_sel_hi:[1,0]
	v_pk_mul_f32 v[26:27], v[6:7], v[30:31]
	v_pk_mul_f32 v[24:25], v[4:5], v[28:29]
	v_pk_mul_f32 v[30:31], v[2:3], v[40:41]
	v_pk_mul_f32 v[28:29], v[0:1], v[44:45]
	global_store_dwordx4 v[42:43], v[24:27], off
	global_store_dwordx4 v[42:43], v[28:31], off offset:16
	ds_read_b32 v24, v150 offset:4800
	v_lshlrev_b64 v[26:27], 12, v[164:165]
	v_lshl_add_u64 v[40:41], v[146:147], 0, v[26:27]
	s_waitcnt lgkmcnt(0)
; __device__ __forceinline__ unsigned cvt_pk_bf16(float lo, float hi) { unsigned r; asm volatile("v_cvt_pk_bf16_f32 %0, %1, %2" : "=v"(r) : "v"(lo), "v"(hi)); return r; }
;     __device__ __forceinline__ void fused(f32x4 (&acc)[2][2][4][2], const Unit& u, int wr, int wc, int fr, int fq, LAS unsigned char* lds, int tid) const {
;     ...
;         for (int bj = 0; bj < 2; ++bj) { const int c = col0 + bj * HALF;
;             const f32x4 g0 = *(const f32x4*)(g + c), g1 = *(const f32x4*)(g + c + 4);
;             f32x4 sc0 = {0.f, 0.f, 0.f, 0.f}, sc1 = sc0, sh0 = sc0, sh1 = sc0;
;             if (MODE == 0) { sc0 = *(const f32x4*)(scale + (size_t)cls * MODLD + c) + 1.0f; sc1 = *(const f32x4*)(scale + (size_t)cls * MODLD + c + 4) + 1.0f;
;                 sh0 = *(const f32x4*)(shift + (size_t)cls * MODLD + c); sh1 = *(const f32x4*)(shift + (size_t)cls * MODLD + c + 4); }
; #pragma unroll
;             for (int ai = 0; ai < 2; ++ai)
; #pragma unroll
;                 for (int m = 0; m < 4; ++m) { const int r = ai * HALF + wr * 64 + m * 16 + fr; const size_t off = (size_t)r * DM + c; const float rs = S[r];
;                     const f32x4 x0 = acc[ai][bj][m][0], x1 = acc[ai][bj][m][1]; const f32x4 y0 = x0 * rs * g0, y1 = x1 * rs * g1;
;                     if (MODE == 0) { { u32x4 wx; wx.x = cvt_pk_bf16(x0[0], x0[1]); wx.y = cvt_pk_bf16(x0[2], x0[3]); wx.z = cvt_pk_bf16(x1[0], x1[1]); wx.w = cvt_pk_bf16(x1[2], x1[3]); *(u32x4*)(xb_ + off) = wx; }
;                         const f32x4 z0 = y0 * sc0 + sh0, z1 = y1 * sc1 + sh1;
;                         u32x4 w; w.x = cvt_pk_bf16(z0[0], z0[1]); w.y = cvt_pk_bf16(z0[2], z0[3]); w.z = cvt_pk_bf16(z1[0], z1[1]); w.w = cvt_pk_bf16(z1[2], z1[3]);
;                         *(u32x4*)(XN + (size_t)u.pm * BM * DM + off) = w; }
;                     else { *(f32x4*)(out_ + off) = y0; *(f32x4*)(out_ + off + 4) = y1; } }
;             asm volatile("" ::: "memory"); }
;         asm volatile("s_waitcnt lgkmcnt(0)" ::: "memory"); __builtin_amdgcn_s_barrier(); asm volatile("" ::: "memory");
	v_pk_mul_f32 v[26:27], v[160:161], v[24:25] op_sel_hi:[1,0]
	v_pk_mul_f32 v[28:29], v[156:157], v[24:25] op_sel_hi:[1,0]
	v_pk_mul_f32 v[30:31], v[154:155], v[24:25] op_sel_hi:[1,0]
	v_pk_mul_f32 v[24:25], v[148:149], v[24:25] op_sel_hi:[1,0]
	v_pk_mul_f32 v[6:7], v[6:7], v[28:29]
	v_pk_mul_f32 v[4:5], v[4:5], v[26:27]
	v_pk_mul_f32 v[2:3], v[2:3], v[24:25]
	v_pk_mul_f32 v[0:1], v[0:1], v[30:31]
	global_store_dwordx4 v[40:41], v[4:7], off
	global_store_dwordx4 v[40:41], v[0:3], off offset:16
	global_load_dwordx4 v[0:3], v[132:133], off offset:512
	global_load_dwordx4 v[4:7], v[132:133], off offset:528
	ds_read_b32 v24, v150 offset:4096
	s_waitcnt lgkmcnt(0)
	v_pk_mul_f32 v[28:29], v[116:117], v[24:25] op_sel_hi:[1,0]
	v_pk_mul_f32 v[26:27], v[118:119], v[24:25] op_sel_hi:[1,0]
	v_pk_mul_f32 v[44:45], v[112:113], v[24:25] op_sel_hi:[1,0]
	v_pk_mul_f32 v[30:31], v[114:115], v[24:25] op_sel_hi:[1,0]
	s_waitcnt vmcnt(0)
	v_pk_mul_f32 v[26:27], v[2:3], v[26:27]
	v_pk_mul_f32 v[24:25], v[0:1], v[28:29]
	v_pk_mul_f32 v[30:31], v[6:7], v[30:31]
	v_pk_mul_f32 v[28:29], v[4:5], v[44:45]
	global_store_dwordx4 v[128:129], v[24:27], off offset:512
	global_store_dwordx4 v[128:129], v[28:31], off offset:528
	ds_read_b32 v24, v150 offset:4160
	s_waitcnt lgkmcnt(0)
	v_pk_mul_f32 v[26:27], v[102:103], v[24:25] op_sel_hi:[1,0]
	v_pk_mul_f32 v[28:29], v[100:101], v[24:25] op_sel_hi:[1,0]
	v_pk_mul_f32 v[44:45], v[96:97], v[24:25] op_sel_hi:[1,0]
	v_pk_mul_f32 v[30:31], v[98:99], v[24:25] op_sel_hi:[1,0]
	v_pk_mul_f32 v[26:27], v[2:3], v[26:27]
	v_pk_mul_f32 v[24:25], v[0:1], v[28:29]
	v_pk_mul_f32 v[30:31], v[6:7], v[30:31]
	v_pk_mul_f32 v[28:29], v[4:5], v[44:45]
	global_store_dwordx4 v[120:121], v[24:27], off offset:512
	global_store_dwordx4 v[120:121], v[28:31], off offset:528
	ds_read_b32 v24, v150 offset:4224
	s_waitcnt lgkmcnt(0)
	v_pk_mul_f32 v[26:27], v[86:87], v[24:25] op_sel_hi:[1,0]
	v_pk_mul_f32 v[28:29], v[84:85], v[24:25] op_sel_hi:[1,0]
	v_pk_mul_f32 v[44:45], v[80:81], v[24:25] op_sel_hi:[1,0]
	v_pk_mul_f32 v[30:31], v[82:83], v[24:25] op_sel_hi:[1,0]
	v_pk_mul_f32 v[26:27], v[2:3], v[26:27]
	v_pk_mul_f32 v[24:25], v[0:1], v[28:29]
	v_pk_mul_f32 v[30:31], v[6:7], v[30:31]
	v_pk_mul_f32 v[28:29], v[4:5], v[44:45]
	global_store_dwordx4 v[104:105], v[24:27], off offset:512
	global_store_dwordx4 v[104:105], v[28:31], off offset:528
	ds_read_b32 v24, v150 offset:4288
	s_waitcnt lgkmcnt(0)
	v_pk_mul_f32 v[26:27], v[70:71], v[24:25] op_sel_hi:[1,0]
	v_pk_mul_f32 v[28:29], v[68:69], v[24:25] op_sel_hi:[1,0]
	v_pk_mul_f32 v[44:45], v[64:65], v[24:25] op_sel_hi:[1,0]
	v_pk_mul_f32 v[30:31], v[66:67], v[24:25] op_sel_hi:[1,0]
	v_pk_mul_f32 v[26:27], v[2:3], v[26:27]
	v_pk_mul_f32 v[24:25], v[0:1], v[28:29]
	v_pk_mul_f32 v[30:31], v[6:7], v[30:31]
	v_pk_mul_f32 v[28:29], v[4:5], v[44:45]
	global_store_dwordx4 v[88:89], v[24:27], off offset:512
	global_store_dwordx4 v[88:89], v[28:31], off offset:528
	ds_read_b32 v24, v150 offset:4608
	s_waitcnt lgkmcnt(0)
	v_pk_mul_f32 v[26:27], v[54:55], v[24:25] op_sel_hi:[1,0]
	v_pk_mul_f32 v[28:29], v[52:53], v[24:25] op_sel_hi:[1,0]
	v_pk_mul_f32 v[44:45], v[48:49], v[24:25] op_sel_hi:[1,0]
	v_pk_mul_f32 v[30:31], v[50:51], v[24:25] op_sel_hi:[1,0]
	v_pk_mul_f32 v[26:27], v[2:3], v[26:27]
	v_pk_mul_f32 v[24:25], v[0:1], v[28:29]
	v_pk_mul_f32 v[30:31], v[6:7], v[30:31]
	v_pk_mul_f32 v[28:29], v[4:5], v[44:45]
	global_store_dwordx4 v[72:73], v[24:27], off offset:512
	global_store_dwordx4 v[72:73], v[28:31], off offset:528
	ds_read_b32 v24, v150 offset:4672
	s_waitcnt lgkmcnt(0)
	v_pk_mul_f32 v[26:27], v[38:39], v[24:25] op_sel_hi:[1,0]
	v_pk_mul_f32 v[28:29], v[36:37], v[24:25] op_sel_hi:[1,0]
	v_pk_mul_f32 v[32:33], v[32:33], v[24:25] op_sel_hi:[1,0]
	v_pk_mul_f32 v[30:31], v[34:35], v[24:25] op_sel_hi:[1,0]
	v_pk_mul_f32 v[26:27], v[2:3], v[26:27]
	v_pk_mul_f32 v[24:25], v[0:1], v[28:29]
	v_pk_mul_f32 v[30:31], v[6:7], v[30:31]
	v_pk_mul_f32 v[28:29], v[4:5], v[32:33]
	global_store_dwordx4 v[58:59], v[24:27], off offset:512
	global_store_dwordx4 v[58:59], v[28:31], off offset:528
	ds_read_b32 v24, v150 offset:4736
	s_waitcnt lgkmcnt(0)
	v_pk_mul_f32 v[20:21], v[20:21], v[24:25] op_sel_hi:[1,0]
	v_pk_mul_f32 v[22:23], v[22:23], v[24:25] op_sel_hi:[1,0]
	v_pk_mul_f32 v[26:27], v[16:17], v[24:25] op_sel_hi:[1,0]
	v_pk_mul_f32 v[24:25], v[18:19], v[24:25] op_sel_hi:[1,0]
	v_pk_mul_f32 v[18:19], v[2:3], v[22:23]
	v_pk_mul_f32 v[16:17], v[0:1], v[20:21]
	v_pk_mul_f32 v[22:23], v[6:7], v[24:25]
	v_pk_mul_f32 v[20:21], v[4:5], v[26:27]
	global_store_dwordx4 v[42:43], v[16:19], off offset:512
	global_store_dwordx4 v[42:43], v[20:23], off offset:528
	ds_read_b32 v16, v150 offset:4800
	s_waitcnt lgkmcnt(0)
	v_pk_mul_f32 v[12:13], v[12:13], v[16:17] op_sel_hi:[1,0]
	v_pk_mul_f32 v[8:9], v[8:9], v[16:17] op_sel_hi:[1,0]
	v_pk_mul_f32 v[14:15], v[14:15], v[16:17] op_sel_hi:[1,0]
	v_pk_mul_f32 v[10:11], v[10:11], v[16:17] op_sel_hi:[1,0]
	v_pk_mul_f32 v[2:3], v[2:3], v[8:9]
	v_pk_mul_f32 v[0:1], v[0:1], v[12:13]
	v_pk_mul_f32 v[6:7], v[6:7], v[10:11]
	v_pk_mul_f32 v[4:5], v[4:5], v[14:15]
	global_store_dwordx4 v[40:41], v[0:3], off offset:512
	global_store_dwordx4 v[40:41], v[4:7], off offset:528
	s_waitcnt lgkmcnt(0)
	s_barrier
